# v60 plus diff-attention item: the next-ticket atomic is awaited where the ticket is published (after the last tile), not right after issue
# baseline (speedup 1.0000x reference)
; #define ALDS __attribute__((address_space(3)))
; __device__ __forceinline__ int diff_item(ldsp lds, int qt, int bh, bool pre, unsigned* nctr, const bf16* U, bf16* O, const float* subw, float lam, float omlinit, float M0, int wave, int lane) {
;     ...
;         unsigned nt = 0u; if (wave == 0 && lane == 0) nt = atomicAdd(nctr, 1u);
;         if (wq >= 2) attn_pair<true, false>(o, lsum, qf, LA, lds0 + stage, lds0 + stage + 32768, lds0 + stage + 16384, lds0 + stage + 32768 + 16384, nslope2, -M0, (float)(t0 + r - 128 * qt - 4 * hh), (float)(t0 + r - 128 * qt - 64 - 4 * hh));
;         else attn_tile<4, true>(o, lsum, qf, LA, lds0 + stage, lds0 + stage + 32768, nslope2, -M0, (float)(t0 + r - 128 * qt - 4 * hh));
;         if (wave == 0 && lane == 0) ((ALDS unsigned*)(lds + CTL_OFF))[3] = nt;
.LBB0_810:
	v_mov_b32_e32 v193, 0
	s_and_saveexec_b64 s[70:71], s[12:13]
	s_cbranch_execz .LBB0_814
	s_mov_b64 s[74:75], exec
	v_mbcnt_lo_u32_b32 v64, s74, 0
	v_mbcnt_hi_u32_b32 v64, s75, v64
	v_mov_b32_e32 v255, v64
	v_cmp_eq_u32_e32 vcc, 0, v64
	s_and_saveexec_b64 s[72:73], vcc
	s_cbranch_execz .LBB0_813
	s_bcnt1_i32_b64 s14, s[74:75]
	v_mov_b32_e32 v65, s14
	global_atomic_add v254, v157, v65, s[68:69] sc0
.LBB0_813:
	s_or_b64 exec, exec, s[72:73]
.LBB0_814:
	s_or_b64 exec, exec, s[70:71]
	s_lshl_b32 s14, s80, 16
	s_and_b32 s72, s14, 0x10000
	s_add_i32 s72, s72, 0
	s_add_i32 s24, s72, 0x8000
	s_mov_b64 s[70:71], -1
	s_and_b64 vcc, exec, s[34:35]
	s_cbranch_vccnz .LBB0_824
	s_andn2_b64 vcc, exec, s[70:71]
	s_cbranch_vccz .LBB0_825

; #define ALDS __attribute__((address_space(3)))
; __device__ __forceinline__ int diff_item(ldsp lds, int qt, int bh, bool pre, unsigned* nctr, const bf16* U, bf16* O, const float* subw, float lam, float omlinit, float M0, int wave, int lane) {
;     ...
;         unsigned nt = 0u; if (wave == 0 && lane == 0) nt = atomicAdd(nctr, 1u);
;         if (wq >= 2) attn_pair<true, false>(o, lsum, qf, LA, lds0 + stage, lds0 + stage + 32768, lds0 + stage + 16384, lds0 + stage + 32768 + 16384, nslope2, -M0, (float)(t0 + r - 128 * qt - 4 * hh), (float)(t0 + r - 128 * qt - 64 - 4 * hh));
;         else attn_tile<4, true>(o, lsum, qf, LA, lds0 + stage, lds0 + stage + 32768, nslope2, -M0, (float)(t0 + r - 128 * qt - 4 * hh));
;         if (wave == 0 && lane == 0) ((ALDS unsigned*)(lds + CTL_OFF))[3] = nt;
.LBB0_817:
	s_waitcnt vmcnt(0)
	v_readfirstlane_b32 s98, v254
	s_nop 1
	v_add_u32_e32 v193, s98, v255
	v_mov_b32_e32 v0, s31
	ds_write_b32 v0, v193

; #define ALDS __attribute__((address_space(3)))
; template <int NET, bool BIAS>
; __device__ __forceinline__ void attn_tile(f32x16 (&o)[NET], float& lsum, const bf16x8 (&qf)[4], const LaneAddr& A, unsigned kimg, unsigned vimg, float nslope2, float negM0, float dt) {
;     bf16x8 kf[2][4];
; #pragma unroll
;     for (int ks = 0; ks < 4; ++ks) { const unsigned ka = A.kb[ks] + kimg;
;         kf[0][ks] = *(const ALDS bf16x8*)(size_t)(ka); kf[1][ks] = *(const ALDS bf16x8*)(size_t)(ka + 8192u); }
;     f32x16 s[2];
; #pragma unroll
;     for (int sub = 0; sub < 2; ++sub) {
;         if (BIAS) { const float d0 = dt - 32.0f * (float)sub;
; #pragma unroll
;             for (int i = 0; i < 16; ++i) s[sub][i] = fmaf(nslope2, fabsf(d0 - (float)((i & 3) + 8 * (i >> 2))), negM0);
;         } else {
; #pragma unroll
;             for (int i = 0; i < 16; ++i) s[sub][i] = negM0;
;         }
;     }
; #pragma unroll
;     for (int ks = 0; ks < 4; ++ks) { s[0] = __builtin_amdgcn_mfma_f32_32x32x16_bf16(kf[0][ks], qf[ks], s[0], 0, 0, 0); s[1] = __builtin_amdgcn_mfma_f32_32x32x16_bf16(kf[1][ks], qf[ks], s[1], 0, 0, 0); }
.LBB0_824:
	v_subrev_u32_e32 v64, s78, v207
	v_add_u32_e32 v64, s79, v64
	v_cvt_f32_i32_e32 v92, v64
	v_add_u32_e32 v64, s72, v167
	ds_read_b128 v[96:99], v64
	ds_read_b128 v[80:83], v64 offset:8192
	v_add_u32_e32 v114, s72, v169
	v_add_f32_e32 v64, 0xc2000000, v92
	v_add_f32_e32 v65, -1.0, v64
	v_pk_add_f32 v[66:67], v[64:65], s[56:57] op_sel_hi:[0,1]
	v_pk_add_f32 v[68:69], v[64:65], s[54:55] op_sel_hi:[0,1]
	v_pk_add_f32 v[70:71], v[64:65], s[58:59] op_sel_hi:[0,1]
	v_pk_add_f32 v[72:73], v[64:65], s[60:61] op_sel_hi:[0,1]
	v_pk_add_f32 v[74:75], v[64:65], s[62:63] op_sel_hi:[0,1]
	v_pk_add_f32 v[76:77], v[64:65], s[64:65] op_sel_hi:[0,1]
	v_pk_add_f32 v[78:79], v[64:65], s[66:67] op_sel_hi:[0,1]
	v_and_b32_e32 v67, 0x7fffffff, v67
	v_and_b32_e32 v66, 0x7fffffff, v66
	v_and_b32_e32 v69, 0x7fffffff, v69
	v_and_b32_e32 v68, 0x7fffffff, v68
	v_and_b32_e32 v71, 0x7fffffff, v71
	v_and_b32_e32 v70, 0x7fffffff, v70
	v_and_b32_e32 v73, 0x7fffffff, v73
	v_and_b32_e32 v72, 0x7fffffff, v72
	v_and_b32_e32 v75, 0x7fffffff, v75
	v_and_b32_e32 v74, 0x7fffffff, v74
	v_and_b32_e32 v77, 0x7fffffff, v77
	v_and_b32_e32 v76, 0x7fffffff, v76
	v_and_b32_e32 v79, 0x7fffffff, v79
	v_and_b32_e32 v78, 0x7fffffff, v78
	v_and_b32_e32 v64, 0x7fffffff, v64
	v_and_b32_e32 v65, 0x7fffffff, v65
	ds_read_b128 v[84:87], v114 offset:8192
	v_pk_fma_f32 v[78:79], v[200:201], v[78:79], v[190:191] op_sel_hi:[0,1,1]
	v_pk_fma_f32 v[76:77], v[200:201], v[76:77], v[188:189] op_sel_hi:[0,1,1]
	v_pk_fma_f32 v[74:75], v[200:201], v[74:75], v[186:187] op_sel_hi:[0,1,1]
	v_pk_fma_f32 v[72:73], v[200:201], v[72:73], v[184:185] op_sel_hi:[0,1,1]
	v_pk_fma_f32 v[70:71], v[200:201], v[70:71], v[182:183] op_sel_hi:[0,1,1]
	v_pk_fma_f32 v[68:69], v[200:201], v[68:69], v[180:181] op_sel_hi:[0,1,1]
	v_pk_fma_f32 v[66:67], v[200:201], v[66:67], v[178:179] op_sel_hi:[0,1,1]
	v_pk_fma_f32 v[64:65], v[200:201], v[64:65], v[174:175] op_sel_hi:[0,1,1]
	v_add_u32_e32 v115, s72, v171
	ds_read_b128 v[88:91], v115 offset:8192
	s_waitcnt lgkmcnt(2)
	v_mfma_f32_32x32x16_bf16 v[64:79], v[80:83], v[140:143], v[64:79]
	v_add_f32_e32 v93, -1.0, v92
	v_add_f32_e64 v94, v92, s56
	v_add_f32_e64 v95, v92, s57
	v_add_f32_e64 v104, v92, s54
	v_add_f32_e64 v105, v92, s55
	v_pk_add_f32 v[106:107], v[92:93], s[58:59] op_sel_hi:[0,1]
	v_pk_add_f32 v[80:81], v[92:93], s[60:61] op_sel_hi:[0,1]
	v_pk_add_f32 v[82:83], v[92:93], s[62:63] op_sel_hi:[0,1]
	v_pk_add_f32 v[108:109], v[92:93], s[64:65] op_sel_hi:[0,1]
	s_waitcnt lgkmcnt(1)
	v_mfma_f32_32x32x16_bf16 v[64:79], v[84:87], v[136:139], v[64:79]
	v_add_f32_e64 v110, v92, s66
	v_add_f32_e64 v111, v92, s67
	v_and_b32_e32 v113, 0x7fffffff, v95
	v_and_b32_e32 v112, 0x7fffffff, v94
	v_and_b32_e32 v105, 0x7fffffff, v105
	v_and_b32_e32 v104, 0x7fffffff, v104
	v_and_b32_e32 v85, 0x7fffffff, v107
	v_and_b32_e32 v84, 0x7fffffff, v106
	v_and_b32_e32 v81, 0x7fffffff, v81
	v_and_b32_e32 v80, 0x7fffffff, v80
	v_and_b32_e32 v83, 0x7fffffff, v83
	v_and_b32_e32 v82, 0x7fffffff, v82
	s_waitcnt lgkmcnt(0)
	v_mfma_f32_32x32x16_bf16 v[64:79], v[88:91], v[132:135], v[64:79]
	v_and_b32_e32 v87, 0x7fffffff, v109
	v_and_b32_e32 v86, 0x7fffffff, v108
	v_and_b32_e32 v89, 0x7fffffff, v111
	v_and_b32_e32 v88, 0x7fffffff, v110
	v_and_b32_e32 v106, 0x7fffffff, v92
	v_and_b32_e32 v107, 0x7fffffff, v93
	v_pk_fma_f32 v[94:95], v[200:201], v[88:89], v[190:191] op_sel_hi:[0,1,1]
	v_pk_fma_f32 v[92:93], v[200:201], v[86:87], v[188:189] op_sel_hi:[0,1,1]
	v_pk_fma_f32 v[90:91], v[200:201], v[82:83], v[186:187] op_sel_hi:[0,1,1]
	v_pk_fma_f32 v[88:89], v[200:201], v[80:81], v[184:185] op_sel_hi:[0,1,1]
	v_pk_fma_f32 v[86:87], v[200:201], v[84:85], v[182:183] op_sel_hi:[0,1,1]
	v_pk_fma_f32 v[84:85], v[200:201], v[104:105], v[180:181] op_sel_hi:[0,1,1]
	v_pk_fma_f32 v[82:83], v[200:201], v[112:113], v[178:179] op_sel_hi:[0,1,1]
	v_pk_fma_f32 v[80:81], v[200:201], v[106:107], v[174:175] op_sel_hi:[0,1,1]
	v_add_u32_e32 v116, s72, v173
	ds_read_b128 v[100:103], v116 offset:8192
	v_mfma_f32_32x32x16_bf16 v[80:95], v[96:99], v[140:143], v[80:95]
	ds_read_b128 v[96:99], v114
	v_add_u32_e32 v145, s24, v159
	v_add_u32_e32 v150, s24, v202
	v_add_u32_e32 v151, s24, v161
	v_add_u32_e32 v197, s24, v203
	v_add_u32_e32 v199, s24, v163
	v_add_u32_e32 v213, s24, v204
	s_waitcnt lgkmcnt(0)
	v_mfma_f32_32x32x16_bf16 v[80:95], v[96:99], v[136:139], v[80:95]
	v_add_u32_e32 v242, s24, v165
	v_add_u32_e32 v243, s24, v205
	s_nop 0
	v_mfma_f32_32x32x16_bf16 v[64:79], v[100:103], v[128:131], v[64:79]
	ds_read_b128 v[96:99], v115
	ds_read_b128 v[100:103], v116
	s_waitcnt lgkmcnt(1)
	v_mfma_f32_32x32x16_bf16 v[80:95], v[96:99], v[132:135], v[80:95]
	s_nop 7
	v_exp_f32_e32 v64, v64
	v_exp_f32_e32 v65, v65
	v_exp_f32_e32 v66, v66
	v_exp_f32_e32 v67, v67
	v_exp_f32_e32 v68, v68
	v_exp_f32_e32 v69, v69
	v_exp_f32_e32 v70, v70
	s_waitcnt lgkmcnt(0)
; #define TR_ISSUE(dst, addr, OFF) dst = vtr((ldsp)(size_t)((addr) + (unsigned)(OFF)))
; template <int NET, bool BIAS>
; __device__ __forceinline__ void attn_tile(f32x16 (&o)[NET], float& lsum, const bf16x8 (&qf)[4], const LaneAddr& A, unsigned kimg, unsigned vimg, float nslope2, float negM0, float dt) {
;     ...
;     s16x4 vlo[2][NET], vhi[2][NET];
; #pragma unroll
;     for (int et = 0; et < NET; ++et) { TR_ISSUE(vlo[0][et], va[et][0], 0); TR_ISSUE(vhi[0][et], va[et][1], 2048); }
;     bf16x8 pa[2][2];
; #pragma unroll
;     for (int sub = 0; sub < 2; ++sub) {
; #pragma unroll
;         for (int i = 0; i < 16; ++i) { s[sub][i] = __builtin_amdgcn_exp2f(s[sub][i]); lsum += s[sub][i]; }
;         pa[sub][0] = pack8s(s[sub], 0); pa[sub][1] = pack8s(s[sub], 8);
;     }
;     tr_wait<NET>(vlo[0], vhi[0]);
;     __builtin_amdgcn_sched_barrier(0);
; #pragma unroll
;     for (int step = 0; step < 4; ++step) {
;         const int cur = step & 1, nxt = cur ^ 1;
;         if (step < 3) {
; #pragma unroll
;             for (int et = 0; et < NET; ++et) { TR_ISSUE(vlo[nxt][et], va[et][0], 256 * (32 * ((step + 1) >> 1) + 16 * ((step + 1) & 1))); TR_ISSUE(vhi[nxt][et], va[et][1], 256 * (32 * ((step + 1) >> 1) + 16 * ((step + 1) & 1)) + 2048); } }
; #pragma unroll
;         for (int et = 0; et < NET; ++et) {
;             const bf16x8 vf = (bf16x8){vlo[cur][et][0], vlo[cur][et][1], vlo[cur][et][2], vlo[cur][et][3], vhi[cur][et][0], vhi[cur][et][1], vhi[cur][et][2], vhi[cur][et][3]};
;             o[et] = __builtin_amdgcn_mfma_f32_32x32x16_bf16(vf, pa[step >> 1][step & 1], o[et], 0, 0, 0);
;         }
;         if (step < 3) tr_wait<NET>(vlo[nxt], vhi[nxt]);
;         __builtin_amdgcn_sched_barrier(0);
;     }
	v_mfma_f32_32x32x16_bf16 v[80:95], v[100:103], v[128:131], v[80:95]
	v_exp_f32_e32 v71, v71
	v_exp_f32_e32 v244, v72
	ds_read_b64_tr_b16 v[96:97], v145
	ds_read_b64_tr_b16 v[98:99], v150 offset:2048
	ds_read_b64_tr_b16 v[146:147], v151
	ds_read_b64_tr_b16 v[148:149], v197 offset:2048
	ds_read_b64_tr_b16 v[214:215], v199
	ds_read_b64_tr_b16 v[216:217], v213 offset:2048
	ds_read_b64_tr_b16 v[218:219], v242
	ds_read_b64_tr_b16 v[220:221], v243 offset:2048
	v_exp_f32_e32 v245, v73
	v_exp_f32_e32 v246, v74
	v_exp_f32_e32 v247, v75
	v_exp_f32_e32 v248, v76
	v_exp_f32_e32 v80, v80
	v_exp_f32_e32 v81, v81
	v_exp_f32_e32 v82, v82
	v_exp_f32_e32 v83, v83
	v_add_f32_e32 v100, v195, v80
	v_exp_f32_e32 v84, v84
	v_add_f32_e32 v100, v81, v100
	v_exp_f32_e32 v85, v85
	v_add_f32_e32 v100, v82, v100
	v_exp_f32_e32 v86, v86
	v_add_f32_e32 v100, v83, v100
	v_exp_f32_e32 v87, v87
	v_add_f32_e32 v100, v84, v100
	v_exp_f32_e32 v88, v88
	v_add_f32_e32 v100, v85, v100
	v_exp_f32_e32 v89, v89
	v_add_f32_e32 v100, v86, v100
	v_exp_f32_e32 v90, v90
	v_add_f32_e32 v100, v87, v100
	v_exp_f32_e32 v91, v91
	v_add_f32_e32 v100, v88, v100
	v_exp_f32_e32 v92, v92
	v_add_f32_e32 v100, v89, v100
	v_exp_f32_e32 v93, v93
	v_add_f32_e32 v100, v90, v100
	v_exp_f32_e32 v94, v94
	v_add_f32_e32 v100, v91, v100
	v_exp_f32_e32 v95, v95
	v_add_f32_e32 v100, v92, v100
	v_add_f32_e32 v100, v93, v100
	v_add_f32_e32 v100, v94, v100
	v_add_f32_e32 v100, v95, v100
	v_cvt_pk_bf16_f32 v222, v80, v81
	v_add_f32_e32 v80, v64, v100
	v_add_f32_e32 v80, v65, v80
	v_add_f32_e32 v80, v66, v80
	v_add_f32_e32 v80, v67, v80
	v_add_f32_e32 v80, v68, v80
	v_add_f32_e32 v80, v69, v80
	v_add_f32_e32 v80, v70, v80
	v_add_f32_e32 v80, v71, v80
	v_add_f32_e32 v72, v244, v80
	v_add_f32_e32 v72, v245, v72
	v_exp_f32_e32 v249, v77
	v_add_f32_e32 v72, v246, v72
	v_exp_f32_e32 v250, v78
	v_add_f32_e32 v72, v247, v72
	v_exp_f32_e32 v251, v79
	v_add_f32_e32 v72, v248, v72
	v_add_f32_e32 v72, v249, v72
	v_add_f32_e32 v72, v250, v72
	v_add_f32_e32 v144, v251, v72
	v_cvt_pk_bf16_f32 v223, v82, v83
	v_cvt_pk_bf16_f32 v224, v84, v85
	v_cvt_pk_bf16_f32 v225, v86, v87
	v_cvt_pk_bf16_f32 v226, v88, v89
	v_cvt_pk_bf16_f32 v227, v90, v91
	v_cvt_pk_bf16_f32 v228, v92, v93
	v_cvt_pk_bf16_f32 v229, v94, v95
	v_cvt_pk_bf16_f32 v230, v64, v65
	v_cvt_pk_bf16_f32 v231, v66, v67
	v_cvt_pk_bf16_f32 v232, v68, v69
	v_cvt_pk_bf16_f32 v233, v70, v71
	s_waitcnt lgkmcnt(6)
	v_mfma_f32_32x32x16_bf16 v[112:127], v[96:99], v[222:225], v[48:63]
	s_waitcnt lgkmcnt(4)
	v_mfma_f32_32x32x16_bf16 v[96:111], v[146:149], v[222:225], v[32:47]
	ds_read_b64_tr_b16 v[146:147], v145 offset:4096
	s_waitcnt lgkmcnt(3)
	v_mfma_f32_32x32x16_bf16 v[80:95], v[214:217], v[222:225], v[16:31]
	ds_read_b64_tr_b16 v[148:149], v150 offset:6144
	ds_read_b64_tr_b16 v[214:215], v151 offset:4096
	ds_read_b64_tr_b16 v[216:217], v197 offset:6144
	ds_read_b64_tr_b16 v[234:235], v199 offset:4096
	ds_read_b64_tr_b16 v[236:237], v213 offset:6144
	ds_read_b64_tr_b16 v[238:239], v242 offset:4096
	ds_read_b64_tr_b16 v[240:241], v243 offset:6144
	s_waitcnt lgkmcnt(8)
	v_mfma_f32_32x32x16_bf16 v[64:79], v[218:221], v[222:225], v[0:15]
	s_waitcnt lgkmcnt(6)
	v_mfma_f32_32x32x16_bf16 v[112:127], v[146:149], v[226:229], v[112:127]
	ds_read_b64_tr_b16 v[146:147], v145 offset:8192
	s_waitcnt lgkmcnt(5)
	v_mfma_f32_32x32x16_bf16 v[96:111], v[214:217], v[226:229], v[96:111]
	ds_read_b64_tr_b16 v[148:149], v150 offset:10240
	ds_read_b64_tr_b16 v[214:215], v151 offset:8192
	ds_read_b64_tr_b16 v[216:217], v197 offset:10240
	ds_read_b64_tr_b16 v[218:219], v199 offset:8192
	ds_read_b64_tr_b16 v[220:221], v213 offset:10240
	ds_read_b64_tr_b16 v[222:223], v242 offset:8192
	ds_read_b64_tr_b16 v[224:225], v243 offset:10240
	s_waitcnt lgkmcnt(10)
	v_mfma_f32_32x32x16_bf16 v[80:95], v[234:237], v[226:229], v[80:95]
	s_waitcnt lgkmcnt(8)
	v_mfma_f32_32x32x16_bf16 v[64:79], v[238:241], v[226:229], v[64:79]
	s_waitcnt lgkmcnt(6)
	v_mfma_f32_32x32x16_bf16 v[112:127], v[146:149], v[230:233], v[112:127]
	ds_read_b64_tr_b16 v[146:147], v145 offset:12288
	s_waitcnt lgkmcnt(5)
	v_mfma_f32_32x32x16_bf16 v[96:111], v[214:217], v[230:233], v[96:111]
	s_waitcnt lgkmcnt(3)
	v_mfma_f32_32x32x16_bf16 v[80:95], v[218:221], v[230:233], v[80:95]
	ds_read_b64_tr_b16 v[148:149], v150 offset:14336
	ds_read_b64_tr_b16 v[214:215], v151 offset:12288
	ds_read_b64_tr_b16 v[216:217], v197 offset:14336
	ds_read_b64_tr_b16 v[218:219], v199 offset:12288
	ds_read_b64_tr_b16 v[220:221], v213 offset:14336
	ds_read_b64_tr_b16 v[226:227], v242 offset:12288
	ds_read_b64_tr_b16 v[228:229], v243 offset:14336
	s_waitcnt lgkmcnt(8)
	v_mfma_f32_32x32x16_bf16 v[64:79], v[222:225], v[230:233], v[64:79]
	v_cvt_pk_bf16_f32 v222, v244, v245
	v_cvt_pk_bf16_f32 v223, v246, v247
	v_cvt_pk_bf16_f32 v224, v248, v249
	v_cvt_pk_bf16_f32 v225, v250, v251
	s_waitcnt lgkmcnt(6)
	s_nop 0
	v_mfma_f32_32x32x16_bf16 v[112:127], v[146:149], v[222:225], v[112:127]
	s_waitcnt lgkmcnt(4)
	v_mfma_f32_32x32x16_bf16 v[96:111], v[214:217], v[222:225], v[96:111]
	s_waitcnt lgkmcnt(2)
	v_mfma_f32_32x32x16_bf16 v[80:95], v[218:221], v[222:225], v[80:95]
	s_waitcnt lgkmcnt(0)
	v_mfma_f32_32x32x16_bf16 v[64:79], v[226:229], v[222:225], v[64:79]
	s_cbranch_execnz .LBB0_816
; #define ALDS __attribute__((address_space(3)))
; #define MF32(acc, a, b) acc = __builtin_amdgcn_mfma_f32_32x32x16_bf16(a, b, acc, 0, 0, 0)
; #define SBAR0() __builtin_amdgcn_sched_barrier(0)
; __device__ __forceinline__ void bias_tile(f32x16 (&s)[2], float nslope2, float negM0, float dt) {
; #pragma unroll
;     for (int sub = 0; sub < 2; ++sub) { const float d0 = dt - 32.0f * (float)sub;
; #pragma unroll
;         for (int i = 0; i < 16; ++i) s[sub][i] = fmaf(nslope2, fabsf(d0 - (float)((i & 3) + 8 * (i >> 2))), negM0); }
; }
; __device__ __forceinline__ void bias_tile_past(f32x16 (&s)[2], float nslope2, float negM0, float dt) {
;     const float slope2 = -nslope2;
; #pragma unroll
;     for (int sub = 0; sub < 2; ++sub) { const float cb = fmaf(nslope2, dt - 32.0f * (float)sub, negM0);
; #pragma unroll
;         for (int i = 0; i < 16; ++i) asm("v_fmamk_f32 %0, %1, %3, %2" : "=v"(s[sub][i]) : "v"(slope2), "v"(cb), "i"(__builtin_bit_cast(int, (float)((i & 3) + 8 * (i >> 2))))); }
; }
; template <bool PAST, bool PAST1 = PAST>
; __device__ __forceinline__ void attn_pair(f32x16 (&o)[4], float& lsum, const bf16x8 (&qf)[4], const LaneAddr& A, unsigned k0, unsigned v0, unsigned k1, unsigned v1, float nslope2, float negM0, float dt0, float dt1) {
;     bf16x8 kf[2][4];
;     f32x16 s0[2], s1[2];
;     bf16x8 pa0[2][2], pa1[2][2];
;     s16x4 vlo[2][4], vhi[2][4];
; #pragma unroll
;     for (int ks = 0; ks < 4; ++ks) { const unsigned ka = A.kb[ks] + k0; kf[0][ks] = *(const ALDS bf16x8*)(size_t)(ka); kf[1][ks] = *(const ALDS bf16x8*)(size_t)(ka + 8192u); }
;     if (PAST) bias_tile_past(s0, nslope2, negM0, dt0); else bias_tile(s0, nslope2, negM0, dt0);
; #pragma unroll
;     for (int ks = 0; ks < 4; ++ks) { MF32(s0[0], kf[0][ks], qf[ks]); MF32(s0[1], kf[1][ks], qf[ks]); }
;     SBAR0();
;     if (PAST1) bias_tile_past(s1, nslope2, negM0, dt1); else bias_tile(s1, nslope2, negM0, dt1);
;     unsigned va0[4][2];
; #pragma unroll
;     for (int et = 0; et < 4; ++et) { va0[et][0] = A.vb[2 * et] + v0; va0[et][1] = A.vb[2 * et + 1] + v0; }
;     bf16x8 k2[2][2];
;     { const unsigned ka = A.kb[0] + k1; k2[0][0] = *(const ALDS bf16x8*)(size_t)(ka); k2[0][1] = *(const ALDS bf16x8*)(size_t)(ka + 8192u); }
;     SBAR0();
.LBB0_825:
	s_nop 10
	v_or_b32_e32 v64, s79, v154
	v_subrev_u32_e32 v65, s78, v206
	v_add_u32_e32 v64, v64, v65
	v_cvt_f32_i32_e32 v65, v64
	v_add_u32_e32 v66, s72, v167
	ds_read_b128 v[70:73], v66
	ds_read_b128 v[74:77], v66 offset:8192
	v_add_u32_e32 v78, s72, v169
	v_add_u32_e32 v82, s72, v171
	v_add_u32_e32 v86, s72, v173
	v_fma_f32 v91, v200, v65, v174
	v_add_f32_e32 v65, 0xc2000000, v65
	ds_read_b128 v[66:69], v78
	ds_read_b128 v[78:81], v78 offset:8192
	ds_read_b128 v[148:151], v82
	ds_read_b128 v[82:85], v82 offset:8192
	ds_read_b128 v[144:147], v86
	ds_read_b128 v[86:89], v86 offset:8192
	v_xor_b32_e32 v90, 0x80000000, v200
	v_fmamk_f32 v112, v90, 0, v91
	v_fmamk_f32 v113, v90, 0x3f800000, v91
	v_fmamk_f32 v114, v90, 0x40000000, v91
	v_fmamk_f32 v115, v90, 0x40400000, v91
	v_fmamk_f32 v116, v90, 0x41000000, v91
	v_fmamk_f32 v117, v90, 0x41100000, v91
	v_fmamk_f32 v118, v90, 0x41200000, v91
	v_fmamk_f32 v119, v90, 0x41300000, v91
	v_fmamk_f32 v120, v90, 0x41800000, v91
	v_fmamk_f32 v121, v90, 0x41880000, v91
	v_fmamk_f32 v122, v90, 0x41900000, v91
	v_fmamk_f32 v123, v90, 0x41980000, v91
	v_fmamk_f32 v124, v90, 0x41c00000, v91
	v_fmamk_f32 v125, v90, 0x41c80000, v91
	v_fmamk_f32 v126, v90, 0x41d00000, v91
	v_fmamk_f32 v127, v90, 0x41d80000, v91
	v_fma_f32 v65, v200, v65, v174
	v_fmamk_f32 v96, v90, 0, v65
	v_fmamk_f32 v97, v90, 0x3f800000, v65
	v_fmamk_f32 v98, v90, 0x40000000, v65
	v_fmamk_f32 v99, v90, 0x40400000, v65
	v_fmamk_f32 v100, v90, 0x41000000, v65
	v_fmamk_f32 v101, v90, 0x41100000, v65
	v_fmamk_f32 v102, v90, 0x41200000, v65
	v_fmamk_f32 v103, v90, 0x41300000, v65
	v_fmamk_f32 v104, v90, 0x41800000, v65
	v_fmamk_f32 v105, v90, 0x41880000, v65
	v_fmamk_f32 v106, v90, 0x41900000, v65
	v_fmamk_f32 v107, v90, 0x41980000, v65
	v_fmamk_f32 v108, v90, 0x41c00000, v65
	v_fmamk_f32 v109, v90, 0x41c80000, v65
	v_fmamk_f32 v110, v90, 0x41d00000, v65
	v_fmamk_f32 v111, v90, 0x41d80000, v65
	v_subrev_u32_e32 v64, 64, v64
	s_waitcnt lgkmcnt(6)
	v_mfma_f32_32x32x16_bf16 v[96:111], v[74:77], v[140:143], v[96:111]
	v_cvt_f32_i32_e32 v64, v64
	s_add_i32 s71, s72, 0x4000
	s_add_i32 s70, s72, 0xc000
	s_waitcnt lgkmcnt(4)
	v_mfma_f32_32x32x16_bf16 v[96:111], v[78:81], v[136:139], v[96:111]
	s_waitcnt lgkmcnt(2)
	v_mfma_f32_32x32x16_bf16 v[96:111], v[82:85], v[132:135], v[96:111]
	s_waitcnt lgkmcnt(0)
	v_mfma_f32_32x32x16_bf16 v[96:111], v[86:89], v[128:131], v[96:111]
	v_mfma_f32_32x32x16_bf16 v[112:127], v[70:73], v[140:143], v[112:127]
	v_add_f32_e32 v65, -1.0, v64
	v_add_f32_e64 v80, v64, s60
	v_add_f32_e64 v81, v64, s61
	v_add_f32_e64 v74, v64, s56
	v_add_f32_e64 v75, v64, s57
	v_pk_add_f32 v[76:77], v[64:65], s[54:55] op_sel_hi:[0,1]
	v_pk_add_f32 v[78:79], v[64:65], s[58:59] op_sel_hi:[0,1]
	v_pk_add_f32 v[82:83], v[64:65], s[62:63] op_sel_hi:[0,1]
	v_pk_add_f32 v[84:85], v[64:65], s[64:65] op_sel_hi:[0,1]
	v_mfma_f32_32x32x16_bf16 v[112:127], v[66:69], v[136:139], v[112:127]
	v_add_f32_e64 v86, v64, s66
	v_add_f32_e64 v87, v64, s67
	v_and_b32_e32 v88, 0x7fffffff, v80
	v_and_b32_e32 v80, 0x7fffffff, v64
	v_add_f32_e32 v64, 0xc2000000, v64
	v_and_b32_e32 v77, 0x7fffffff, v77
	v_and_b32_e32 v76, 0x7fffffff, v76
	v_and_b32_e32 v89, 0x7fffffff, v81
	v_mfma_f32_32x32x16_bf16 v[112:127], v[148:151], v[132:135], v[112:127]
	v_and_b32_e32 v85, 0x7fffffff, v85
	v_and_b32_e32 v84, 0x7fffffff, v84
	v_and_b32_e32 v81, 0x7fffffff, v65
	v_add_f32_e32 v65, -1.0, v64
	v_and_b32_e32 v75, 0x7fffffff, v75
	v_and_b32_e32 v74, 0x7fffffff, v74
	v_and_b32_e32 v79, 0x7fffffff, v79
	v_mfma_f32_32x32x16_bf16 v[112:127], v[144:147], v[128:131], v[112:127]
	v_and_b32_e32 v78, 0x7fffffff, v78
	v_and_b32_e32 v83, 0x7fffffff, v83
	v_and_b32_e32 v82, 0x7fffffff, v82
	v_and_b32_e32 v87, 0x7fffffff, v87
	v_and_b32_e32 v86, 0x7fffffff, v86
	v_pk_fma_f32 v[92:93], v[200:201], v[84:85], v[188:189] op_sel_hi:[0,1,1]
	v_pk_fma_f32 v[84:85], v[200:201], v[76:77], v[180:181] op_sel_hi:[0,1,1]
	v_pk_add_f32 v[76:77], v[64:65], s[54:55] op_sel_hi:[0,1]
	v_pk_add_f32 v[214:215], v[64:65], s[60:61] op_sel_hi:[0,1]
	v_pk_add_f32 v[218:219], v[64:65], s[64:65] op_sel_hi:[0,1]
	v_pk_fma_f32 v[94:95], v[200:201], v[86:87], v[190:191] op_sel_hi:[0,1,1]
	v_pk_fma_f32 v[90:91], v[200:201], v[82:83], v[186:187] op_sel_hi:[0,1,1]
	v_pk_fma_f32 v[86:87], v[200:201], v[78:79], v[182:183] op_sel_hi:[0,1,1]
	v_pk_fma_f32 v[82:83], v[200:201], v[74:75], v[178:179] op_sel_hi:[0,1,1]
	v_pk_add_f32 v[74:75], v[64:65], s[56:57] op_sel_hi:[0,1]
	v_pk_add_f32 v[78:79], v[64:65], s[58:59] op_sel_hi:[0,1]
	v_pk_add_f32 v[216:217], v[64:65], s[62:63] op_sel_hi:[0,1]
	v_pk_add_f32 v[220:221], v[64:65], s[66:67] op_sel_hi:[0,1]
	v_and_b32_e32 v224, 0x7fffffff, v76
	v_and_b32_e32 v215, 0x7fffffff, v215
	v_and_b32_e32 v214, 0x7fffffff, v214
	v_and_b32_e32 v76, 0x7fffffff, v218
	v_add_u32_e32 v218, s71, v167
	v_and_b32_e32 v223, 0x7fffffff, v75
	v_and_b32_e32 v222, 0x7fffffff, v74
	v_and_b32_e32 v225, 0x7fffffff, v77
	v_and_b32_e32 v227, 0x7fffffff, v79
	v_and_b32_e32 v226, 0x7fffffff, v78
	v_and_b32_e32 v75, 0x7fffffff, v217
	v_and_b32_e32 v74, 0x7fffffff, v216
	v_and_b32_e32 v77, 0x7fffffff, v219
	v_and_b32_e32 v79, 0x7fffffff, v221
	v_and_b32_e32 v78, 0x7fffffff, v220
	v_pk_fma_f32 v[72:73], v[200:201], v[214:215], v[184:185] op_sel_hi:[0,1,1]
	ds_read_b128 v[214:217], v218
	ds_read_b128 v[218:221], v218 offset:8192
	v_and_b32_e32 v64, 0x7fffffff, v64
	v_and_b32_e32 v65, 0x7fffffff, v65
	v_pk_fma_f32 v[80:81], v[200:201], v[80:81], v[174:175] op_sel_hi:[0,1,1]
	v_pk_fma_f32 v[88:89], v[200:201], v[88:89], v[184:185] op_sel_hi:[0,1,1]
	v_pk_fma_f32 v[64:65], v[200:201], v[64:65], v[174:175] op_sel_hi:[0,1,1]
	v_pk_fma_f32 v[78:79], v[200:201], v[78:79], v[190:191] op_sel_hi:[0,1,1]
	v_pk_fma_f32 v[76:77], v[200:201], v[76:77], v[188:189] op_sel_hi:[0,1,1]
	v_pk_fma_f32 v[74:75], v[200:201], v[74:75], v[186:187] op_sel_hi:[0,1,1]
	v_pk_fma_f32 v[70:71], v[200:201], v[226:227], v[182:183] op_sel_hi:[0,1,1]
	v_pk_fma_f32 v[68:69], v[200:201], v[224:225], v[180:181] op_sel_hi:[0,1,1]
	v_pk_fma_f32 v[66:67], v[200:201], v[222:223], v[178:179] op_sel_hi:[0,1,1]
	v_add_u32_e32 v197, s24, v159
	v_add_u32_e32 v199, s24, v202
	v_add_u32_e32 v200, s24, v161
	v_add_u32_e32 v213, s24, v203
	v_add_u32_e32 v148, s24, v163
	v_add_u32_e32 v149, s24, v204
	v_add_u32_e32 v150, s24, v165
	v_add_u32_e32 v151, s24, v205
	s_waitcnt lgkmcnt(1)
; #define ALDS __attribute__((address_space(3)))
; #define SBAR0() __builtin_amdgcn_sched_barrier(0)
; template <bool PAST, bool PAST1 = PAST>
; __device__ __forceinline__ void attn_pair(f32x16 (&o)[4], float& lsum, const bf16x8 (&qf)[4], const LaneAddr& A, unsigned k0, unsigned v0, unsigned k1, unsigned v1, float nslope2, float negM0, float dt0, float dt1) {
;     ...
; #pragma unroll
;     for (int g = 0; g < 8; ++g) {
;         const int ks = g >> 1, sub = g & 1;
;         if (sub == 0 && ks < 3) { const unsigned ka = A.kb[ks + 1] + k1; k2[(ks + 1) & 1][0] = *(const ALDS bf16x8*)(size_t)(ka); k2[(ks + 1) & 1][1] = *(const ALDS bf16x8*)(size_t)(ka + 8192u); }
;         MF32(s1[sub], k2[ks & 1][sub], qf[ks]);
; #pragma unroll
;         for (int k = 0; k < 4; ++k) { const int idx = 4 * g + k; s0[idx >> 4][idx & 15] = __builtin_amdgcn_exp2f(s0[idx >> 4][idx & 15]); lsum += s0[idx >> 4][idx & 15]; }
;         if (g & 1) pa0[g >> 2][(g >> 1) & 1] = pack8s(s0[g >> 2], 8 * ((g >> 1) & 1));
;         if (g == 6) {
; #pragma unroll
;             for (int et = 0; et < 4; ++et) { TR_ISSUE(vlo[0][et], va0[et][0], 0); TR_ISSUE(vhi[0][et], va0[et][1], 2048); } }
;         SBAR0();
;     }
;     tr_wait<4>(vlo[0], vhi[0]);
;     SBAR0();
;     unsigned va1[4][2];
; #pragma unroll
;     for (int g = 0; g < 16; ++g) {
;         const int step = g >> 2, et = g & 3, cur = step & 1, nxt = cur ^ 1;
;         if (et == 0) {
;             if (step < 3) {
; #pragma unroll
;                 for (int e2 = 0; e2 < 4; ++e2) { TR_ISSUE(vlo[nxt][e2], va0[e2][0], 256 * (32 * ((step + 1) >> 1) + 16 * ((step + 1) & 1))); TR_ISSUE(vhi[nxt][e2], va0[e2][1], 256 * (32 * ((step + 1) >> 1) + 16 * ((step + 1) & 1)) + 2048); }
;             } else {
; #pragma unroll
;                 for (int e2 = 0; e2 < 4; ++e2) { va1[e2][0] = A.vb[2 * e2] + v1; va1[e2][1] = A.vb[2 * e2 + 1] + v1; TR_ISSUE(vlo[nxt][e2], va1[e2][0], 0); TR_ISSUE(vhi[nxt][e2], va1[e2][1], 2048); }
;             }
;         }
;         MF32(o[et], VFRAG(cur, et), pa0[step >> 1][step & 1]);
; #pragma unroll
;         for (int k = 0; k < 2; ++k) { const int idx = 2 * g + k; s1[idx >> 4][idx & 15] = __builtin_amdgcn_exp2f(s1[idx >> 4][idx & 15]); lsum += s1[idx >> 4][idx & 15]; }
;         if (et == 3) { pa1[step >> 1][step & 1] = pack8s(s1[step >> 1], 8 * (step & 1)); tr_wait<4>(vlo[nxt], vhi[nxt]); }
;         SBAR0();
;     }
	v_mfma_f32_32x32x16_bf16 v[80:95], v[214:217], v[140:143], v[80:95]
	v_exp_f32_e32 v112, v112
	v_add_u32_e32 v222, s71, v169
	v_exp_f32_e32 v113, v113
	ds_read_b128 v[144:147], v222
	ds_read_b128 v[222:225], v222 offset:8192
	v_exp_f32_e32 v114, v114
	v_exp_f32_e32 v115, v115
	v_add_f32_e32 v195, v195, v112
	v_add_f32_e32 v195, v113, v195
	v_add_f32_e32 v195, v114, v195
	v_add_f32_e32 v195, v115, v195
	s_waitcnt lgkmcnt(2)
	v_mfma_f32_32x32x16_bf16 v[64:79], v[218:221], v[140:143], v[64:79]
	v_exp_f32_e32 v140, v116
	v_exp_f32_e32 v141, v117
	v_exp_f32_e32 v142, v118
	v_exp_f32_e32 v119, v119
	v_add_f32_e32 v116, v140, v195
	v_add_f32_e32 v116, v141, v116
	v_add_f32_e32 v116, v142, v116
	v_add_f32_e32 v195, v119, v116
	v_cvt_pk_bf16_f32 v116, v112, v113
	v_cvt_pk_bf16_f32 v117, v114, v115
	v_cvt_pk_bf16_f32 v118, v140, v141
	v_cvt_pk_bf16_f32 v119, v142, v119
	v_add_u32_e32 v112, s71, v171
	ds_read_b128 v[140:143], v112
	ds_read_b128 v[214:217], v112 offset:8192
	v_exp_f32_e32 v112, v120
	s_waitcnt lgkmcnt(3)
	v_mfma_f32_32x32x16_bf16 v[80:95], v[144:147], v[136:139], v[80:95]
	v_exp_f32_e32 v113, v121
	v_exp_f32_e32 v114, v122
	v_exp_f32_e32 v115, v123
	v_add_f32_e32 v120, v112, v195
	v_add_f32_e32 v120, v113, v120
	v_add_f32_e32 v120, v114, v120
	v_add_f32_e32 v120, v115, v120
	s_waitcnt lgkmcnt(2)
	v_mfma_f32_32x32x16_bf16 v[64:79], v[222:225], v[136:139], v[64:79]
	v_exp_f32_e32 v121, v124
	v_exp_f32_e32 v122, v125
	v_exp_f32_e32 v123, v126
	v_exp_f32_e32 v124, v127
	v_add_f32_e32 v120, v121, v120
	v_add_f32_e32 v120, v122, v120
	v_add_f32_e32 v120, v123, v120
	v_cvt_pk_bf16_f32 v112, v112, v113
	v_cvt_pk_bf16_f32 v113, v114, v115
	v_cvt_pk_bf16_f32 v114, v121, v122
	v_cvt_pk_bf16_f32 v115, v123, v124
	v_add_f32_e32 v136, v124, v120
	s_waitcnt lgkmcnt(1)
	v_mfma_f32_32x32x16_bf16 v[80:95], v[140:143], v[132:135], v[80:95]
	v_exp_f32_e32 v96, v96
	v_add_u32_e32 v124, s71, v173
	v_exp_f32_e32 v97, v97
	ds_read_b128 v[120:123], v124
	ds_read_b128 v[124:127], v124 offset:8192
	v_exp_f32_e32 v98, v98
	v_exp_f32_e32 v99, v99
	v_add_f32_e32 v136, v96, v136
	v_add_f32_e32 v136, v97, v136
	v_add_f32_e32 v136, v98, v136
	v_add_f32_e32 v136, v99, v136
	s_waitcnt lgkmcnt(2)
	v_mfma_f32_32x32x16_bf16 v[64:79], v[214:217], v[132:135], v[64:79]
	v_exp_f32_e32 v132, v100
	v_exp_f32_e32 v133, v101
	v_exp_f32_e32 v134, v102
	v_exp_f32_e32 v103, v103
	v_add_f32_e32 v100, v132, v136
	v_add_f32_e32 v100, v133, v100
	v_add_f32_e32 v100, v134, v100
	v_add_f32_e32 v135, v103, v100
	v_cvt_pk_bf16_f32 v100, v96, v97
	v_cvt_pk_bf16_f32 v101, v98, v99
	v_cvt_pk_bf16_f32 v102, v132, v133
	v_cvt_pk_bf16_f32 v103, v134, v103
	v_exp_f32_e32 v96, v104
	s_waitcnt lgkmcnt(1)
	v_mfma_f32_32x32x16_bf16 v[80:95], v[120:123], v[128:131], v[80:95]
	v_exp_f32_e32 v98, v105
	v_exp_f32_e32 v99, v106
	v_add_f32_e32 v97, v96, v135
	v_exp_f32_e32 v140, v107
	ds_read_b64_tr_b16 v[104:105], v197
	ds_read_b64_tr_b16 v[106:107], v199 offset:2048
	ds_read_b64_tr_b16 v[120:121], v200
	ds_read_b64_tr_b16 v[122:123], v213 offset:2048
	ds_read_b64_tr_b16 v[132:133], v148
	ds_read_b64_tr_b16 v[134:135], v149 offset:2048
	ds_read_b64_tr_b16 v[136:137], v150
	ds_read_b64_tr_b16 v[138:139], v151 offset:2048
	v_add_f32_e32 v97, v98, v97
	v_add_f32_e32 v97, v99, v97
	v_add_f32_e32 v97, v140, v97
	s_waitcnt lgkmcnt(8)
	v_mfma_f32_32x32x16_bf16 v[64:79], v[124:127], v[128:131], v[64:79]
	v_exp_f32_e32 v108, v108
	v_exp_f32_e32 v109, v109
	v_exp_f32_e32 v110, v110
	v_exp_f32_e32 v111, v111
	v_add_f32_e32 v97, v108, v97
	v_add_f32_e32 v97, v109, v97
	v_add_f32_e32 v97, v110, v97
	v_add_f32_e32 v144, v111, v97
	v_cvt_pk_bf16_f32 v96, v96, v98
	v_cvt_pk_bf16_f32 v97, v99, v140
	v_cvt_pk_bf16_f32 v98, v108, v109
	v_cvt_pk_bf16_f32 v99, v110, v111
	ds_read_b64_tr_b16 v[108:109], v197 offset:4096
	ds_read_b64_tr_b16 v[110:111], v199 offset:6144
	ds_read_b64_tr_b16 v[124:125], v200 offset:4096
	ds_read_b64_tr_b16 v[126:127], v213 offset:6144
	ds_read_b64_tr_b16 v[128:129], v148 offset:4096
	ds_read_b64_tr_b16 v[130:131], v149 offset:6144
	ds_read_b64_tr_b16 v[140:141], v150 offset:4096
	ds_read_b64_tr_b16 v[142:143], v151 offset:6144
	v_exp_f32_e32 v80, v80
	v_exp_f32_e32 v81, v81
	s_waitcnt lgkmcnt(14)
	v_mfma_f32_32x32x16_bf16 v[48:63], v[104:107], v[116:119], v[48:63]
	v_add_f32_e32 v104, v80, v144
	v_add_f32_e32 v104, v81, v104
	v_exp_f32_e32 v82, v82
	v_exp_f32_e32 v83, v83
	s_waitcnt lgkmcnt(12)
	v_mfma_f32_32x32x16_bf16 v[32:47], v[120:123], v[116:119], v[32:47]
	v_add_f32_e32 v104, v82, v104
	v_add_f32_e32 v104, v83, v104
	v_exp_f32_e32 v84, v84
	v_exp_f32_e32 v85, v85
	s_waitcnt lgkmcnt(10)
	v_mfma_f32_32x32x16_bf16 v[16:31], v[132:135], v[116:119], v[16:31]
	v_add_f32_e32 v104, v84, v104
	v_add_f32_e32 v104, v85, v104
	v_exp_f32_e32 v86, v86
	v_exp_f32_e32 v87, v87
	v_cvt_pk_bf16_f32 v80, v80, v81
	v_cvt_pk_bf16_f32 v81, v82, v83
	v_add_f32_e32 v104, v86, v104
	v_cvt_pk_bf16_f32 v82, v84, v85
	v_cvt_pk_bf16_f32 v83, v86, v87
	s_waitcnt lgkmcnt(8)
	v_mfma_f32_32x32x16_bf16 v[0:15], v[136:139], v[116:119], v[0:15]
	v_add_f32_e32 v136, v87, v104
	ds_read_b64_tr_b16 v[104:105], v197 offset:8192
	ds_read_b64_tr_b16 v[106:107], v199 offset:10240
	ds_read_b64_tr_b16 v[116:117], v200 offset:8192
	ds_read_b64_tr_b16 v[118:119], v213 offset:10240
	ds_read_b64_tr_b16 v[120:121], v148 offset:8192
	ds_read_b64_tr_b16 v[122:123], v149 offset:10240
	ds_read_b64_tr_b16 v[132:133], v150 offset:8192
	ds_read_b64_tr_b16 v[134:135], v151 offset:10240
	v_exp_f32_e32 v84, v88
	v_exp_f32_e32 v86, v89
	s_waitcnt lgkmcnt(14)
; #define TR_ISSUE(dst, addr, OFF) dst = vtr((ldsp)(size_t)((addr) + (unsigned)(OFF)))
; #define MF32(acc, a, b) acc = __builtin_amdgcn_mfma_f32_32x32x16_bf16(a, b, acc, 0, 0, 0)
; #define SBAR0() __builtin_amdgcn_sched_barrier(0)
; template <bool PAST, bool PAST1 = PAST>
; __device__ __forceinline__ void attn_pair(f32x16 (&o)[4], float& lsum, const bf16x8 (&qf)[4], const LaneAddr& A, unsigned k0, unsigned v0, unsigned k1, unsigned v1, float nslope2, float negM0, float dt0, float dt1) {
;     ...
;     unsigned va1[4][2];
; #pragma unroll
;     for (int g = 0; g < 16; ++g) {
;         const int step = g >> 2, et = g & 3, cur = step & 1, nxt = cur ^ 1;
;         if (et == 0) {
;             if (step < 3) {
; #pragma unroll
;                 for (int e2 = 0; e2 < 4; ++e2) { TR_ISSUE(vlo[nxt][e2], va0[e2][0], 256 * (32 * ((step + 1) >> 1) + 16 * ((step + 1) & 1))); TR_ISSUE(vhi[nxt][e2], va0[e2][1], 256 * (32 * ((step + 1) >> 1) + 16 * ((step + 1) & 1)) + 2048); }
;             } else {
; #pragma unroll
;                 for (int e2 = 0; e2 < 4; ++e2) { va1[e2][0] = A.vb[2 * e2] + v1; va1[e2][1] = A.vb[2 * e2 + 1] + v1; TR_ISSUE(vlo[nxt][e2], va1[e2][0], 0); TR_ISSUE(vhi[nxt][e2], va1[e2][1], 2048); }
;             }
;         }
;         MF32(o[et], VFRAG(cur, et), pa0[step >> 1][step & 1]);
; #pragma unroll
;         for (int k = 0; k < 2; ++k) { const int idx = 2 * g + k; s1[idx >> 4][idx & 15] = __builtin_amdgcn_exp2f(s1[idx >> 4][idx & 15]); lsum += s1[idx >> 4][idx & 15]; }
;         if (et == 3) { pa1[step >> 1][step & 1] = pack8s(s1[step >> 1], 8 * (step & 1)); tr_wait<4>(vlo[nxt], vhi[nxt]); }
;         SBAR0();
;     }
	v_mfma_f32_32x32x16_bf16 v[48:63], v[108:111], v[112:115], v[48:63]
	v_add_f32_e32 v85, v84, v136
	v_add_f32_e32 v85, v86, v85
	v_exp_f32_e32 v87, v90
	v_exp_f32_e32 v88, v91
	s_waitcnt lgkmcnt(12)
	v_mfma_f32_32x32x16_bf16 v[32:47], v[124:127], v[112:115], v[32:47]
	v_add_f32_e32 v85, v87, v85
	v_add_f32_e32 v85, v88, v85
	v_exp_f32_e32 v89, v92
	v_exp_f32_e32 v90, v93
	s_waitcnt lgkmcnt(10)
	v_mfma_f32_32x32x16_bf16 v[16:31], v[128:131], v[112:115], v[16:31]
	v_add_f32_e32 v85, v89, v85
	v_add_f32_e32 v85, v90, v85
	v_exp_f32_e32 v91, v94
	v_exp_f32_e32 v92, v95
	v_cvt_pk_bf16_f32 v84, v84, v86
	v_cvt_pk_bf16_f32 v86, v89, v90
	v_add_f32_e32 v85, v91, v85
	v_add_f32_e32 v124, v92, v85
	v_cvt_pk_bf16_f32 v85, v87, v88
	v_cvt_pk_bf16_f32 v87, v91, v92
	s_waitcnt lgkmcnt(8)
	v_mfma_f32_32x32x16_bf16 v[0:15], v[140:143], v[112:115], v[0:15]
	ds_read_b64_tr_b16 v[88:89], v197 offset:12288
	ds_read_b64_tr_b16 v[90:91], v199 offset:14336
	ds_read_b64_tr_b16 v[92:93], v200 offset:12288
	ds_read_b64_tr_b16 v[94:95], v213 offset:14336
	ds_read_b64_tr_b16 v[108:109], v148 offset:12288
	ds_read_b64_tr_b16 v[110:111], v149 offset:14336
	ds_read_b64_tr_b16 v[112:113], v150 offset:12288
	ds_read_b64_tr_b16 v[114:115], v151 offset:14336
	v_exp_f32_e32 v64, v64
	v_exp_f32_e32 v65, v65
	s_waitcnt lgkmcnt(14)
	v_mfma_f32_32x32x16_bf16 v[48:63], v[104:107], v[100:103], v[48:63]
	v_add_f32_e32 v104, v64, v124
	v_add_f32_e32 v104, v65, v104
	v_exp_f32_e32 v66, v66
	v_exp_f32_e32 v67, v67
	s_waitcnt lgkmcnt(12)
	v_mfma_f32_32x32x16_bf16 v[32:47], v[116:119], v[100:103], v[32:47]
	v_add_f32_e32 v104, v66, v104
	v_add_f32_e32 v104, v67, v104
	v_exp_f32_e32 v68, v68
	v_exp_f32_e32 v69, v69
	s_waitcnt lgkmcnt(10)
	v_mfma_f32_32x32x16_bf16 v[16:31], v[120:123], v[100:103], v[16:31]
	v_add_f32_e32 v104, v68, v104
	v_add_f32_e32 v104, v69, v104
	v_exp_f32_e32 v70, v70
	v_exp_f32_e32 v71, v71
	s_waitcnt lgkmcnt(8)
	v_mfma_f32_32x32x16_bf16 v[0:15], v[132:135], v[100:103], v[0:15]
	v_cvt_pk_bf16_f32 v64, v64, v65
	v_add_f32_e32 v100, v70, v104
	v_add_f32_e32 v120, v71, v100
	v_cvt_pk_bf16_f32 v65, v66, v67
	v_cvt_pk_bf16_f32 v66, v68, v69
	v_cvt_pk_bf16_f32 v67, v70, v71
	v_exp_f32_e32 v129, v72
	v_add_u32_e32 v121, s70, v159
	v_add_u32_e32 v123, s70, v161
	v_add_u32_e32 v125, s70, v163
	v_add_u32_e32 v127, s70, v165
	v_add_u32_e32 v122, s70, v202
	ds_read_b64_tr_b16 v[68:69], v121
	ds_read_b64_tr_b16 v[70:71], v122 offset:2048
	v_add_u32_e32 v124, s70, v203
	ds_read_b64_tr_b16 v[100:101], v123
	ds_read_b64_tr_b16 v[102:103], v124 offset:2048
	v_add_u32_e32 v126, s70, v204
	ds_read_b64_tr_b16 v[104:105], v125
	ds_read_b64_tr_b16 v[106:107], v126 offset:2048
	v_add_u32_e32 v128, s70, v205
	ds_read_b64_tr_b16 v[116:117], v127
	ds_read_b64_tr_b16 v[118:119], v128 offset:2048
	v_add_f32_e32 v72, v129, v120
	v_exp_f32_e32 v120, v73
	s_waitcnt lgkmcnt(14)
	v_mfma_f32_32x32x16_bf16 v[48:63], v[88:91], v[96:99], v[48:63]
	v_add_f32_e32 v72, v120, v72
	s_waitcnt lgkmcnt(12)
	v_mfma_f32_32x32x16_bf16 v[32:47], v[92:95], v[96:99], v[32:47]
	v_exp_f32_e32 v92, v74
	v_exp_f32_e32 v93, v75
	v_add_f32_e32 v72, v92, v72
	v_add_f32_e32 v72, v93, v72
	v_exp_f32_e32 v94, v76
	v_exp_f32_e32 v95, v77
	s_waitcnt lgkmcnt(10)
	v_mfma_f32_32x32x16_bf16 v[16:31], v[108:111], v[96:99], v[16:31]
	v_add_f32_e32 v72, v94, v72
	v_add_f32_e32 v72, v95, v72
	s_waitcnt lgkmcnt(8)
	v_mfma_f32_32x32x16_bf16 v[0:15], v[112:115], v[96:99], v[0:15]
	v_exp_f32_e32 v96, v78
	v_exp_f32_e32 v97, v79
	v_add_f32_e32 v72, v96, v72
	v_add_f32_e32 v144, v97, v72
	s_waitcnt lgkmcnt(6)
; #define TR_ISSUE(dst, addr, OFF) dst = vtr((ldsp)(size_t)((addr) + (unsigned)(OFF)))
; #define MF32(acc, a, b) acc = __builtin_amdgcn_mfma_f32_32x32x16_bf16(a, b, acc, 0, 0, 0)
; #define SBAR0() __builtin_amdgcn_sched_barrier(0)
; template <bool PAST, bool PAST1 = PAST>
; __device__ __forceinline__ void attn_pair(f32x16 (&o)[4], float& lsum, const bf16x8 (&qf)[4], const LaneAddr& A, unsigned k0, unsigned v0, unsigned k1, unsigned v1, float nslope2, float negM0, float dt0, float dt1) {
;     ...
; #pragma unroll
;     for (int step = 0; step < 4; ++step) {
;         const int cur = step & 1, nxt = cur ^ 1;
;         if (step < 3) {
; #pragma unroll
;             for (int e2 = 0; e2 < 4; ++e2) { TR_ISSUE(vlo[nxt][e2], va1[e2][0], 256 * (32 * ((step + 1) >> 1) + 16 * ((step + 1) & 1))); TR_ISSUE(vhi[nxt][e2], va1[e2][1], 256 * (32 * ((step + 1) >> 1) + 16 * ((step + 1) & 1)) + 2048); } }
; #pragma unroll
;         for (int et = 0; et < 4; ++et) MF32(o[et], VFRAG(cur, et), pa1[step >> 1][step & 1]);
;         if (step < 3) tr_wait<4>(vlo[nxt], vhi[nxt]);
;         SBAR0();
;     }
	v_mfma_f32_32x32x16_bf16 v[48:63], v[68:71], v[80:83], v[48:63]
	ds_read_b64_tr_b16 v[68:69], v121 offset:4096
	ds_read_b64_tr_b16 v[70:71], v122 offset:6144
	ds_read_b64_tr_b16 v[72:73], v123 offset:4096
	ds_read_b64_tr_b16 v[74:75], v124 offset:6144
	ds_read_b64_tr_b16 v[76:77], v125 offset:4096
	ds_read_b64_tr_b16 v[78:79], v126 offset:6144
	ds_read_b64_tr_b16 v[88:89], v127 offset:4096
	ds_read_b64_tr_b16 v[90:91], v128 offset:6144
	s_waitcnt lgkmcnt(12)
	v_mfma_f32_32x32x16_bf16 v[32:47], v[100:103], v[80:83], v[32:47]
	s_waitcnt lgkmcnt(10)
	v_mfma_f32_32x32x16_bf16 v[16:31], v[104:107], v[80:83], v[16:31]
	s_waitcnt lgkmcnt(8)
	v_mfma_f32_32x32x16_bf16 v[0:15], v[116:119], v[80:83], v[0:15]
	s_waitcnt lgkmcnt(6)
	v_mfma_f32_32x32x16_bf16 v[48:63], v[68:71], v[84:87], v[48:63]
	ds_read_b64_tr_b16 v[68:69], v121 offset:8192
	s_waitcnt lgkmcnt(5)
	v_mfma_f32_32x32x16_bf16 v[32:47], v[72:75], v[84:87], v[32:47]
	s_waitcnt lgkmcnt(3)
	v_mfma_f32_32x32x16_bf16 v[16:31], v[76:79], v[84:87], v[16:31]
	ds_read_b64_tr_b16 v[70:71], v122 offset:10240
	ds_read_b64_tr_b16 v[72:73], v123 offset:8192
	ds_read_b64_tr_b16 v[74:75], v124 offset:10240
	ds_read_b64_tr_b16 v[76:77], v125 offset:8192
	ds_read_b64_tr_b16 v[78:79], v126 offset:10240
	ds_read_b64_tr_b16 v[80:81], v127 offset:8192
	ds_read_b64_tr_b16 v[82:83], v128 offset:10240
	s_waitcnt lgkmcnt(8)
	v_mfma_f32_32x32x16_bf16 v[0:15], v[88:91], v[84:87], v[0:15]
	s_waitcnt lgkmcnt(6)
	v_mfma_f32_32x32x16_bf16 v[48:63], v[68:71], v[64:67], v[48:63]
	ds_read_b64_tr_b16 v[68:69], v121 offset:12288
	s_waitcnt lgkmcnt(5)
	v_mfma_f32_32x32x16_bf16 v[32:47], v[72:75], v[64:67], v[32:47]
	s_waitcnt lgkmcnt(3)
	v_mfma_f32_32x32x16_bf16 v[16:31], v[76:79], v[64:67], v[16:31]
	ds_read_b64_tr_b16 v[70:71], v122 offset:14336
	ds_read_b64_tr_b16 v[72:73], v123 offset:12288
	ds_read_b64_tr_b16 v[74:75], v124 offset:14336
	ds_read_b64_tr_b16 v[76:77], v125 offset:12288
	ds_read_b64_tr_b16 v[78:79], v126 offset:14336
	ds_read_b64_tr_b16 v[84:85], v127 offset:12288
	ds_read_b64_tr_b16 v[86:87], v128 offset:14336
	s_waitcnt lgkmcnt(8)
	v_mfma_f32_32x32x16_bf16 v[0:15], v[80:83], v[64:67], v[0:15]
	v_cvt_pk_bf16_f32 v64, v129, v120
	v_cvt_pk_bf16_f32 v65, v92, v93
	v_cvt_pk_bf16_f32 v66, v94, v95
	v_cvt_pk_bf16_f32 v67, v96, v97
	s_waitcnt lgkmcnt(6)
	s_nop 0
	v_mfma_f32_32x32x16_bf16 v[48:63], v[68:71], v[64:67], v[48:63]
	s_waitcnt lgkmcnt(4)
	v_mfma_f32_32x32x16_bf16 v[32:47], v[72:75], v[64:67], v[32:47]
	s_waitcnt lgkmcnt(2)
	v_mfma_f32_32x32x16_bf16 v[16:31], v[76:79], v[64:67], v[16:31]
	s_waitcnt lgkmcnt(0)
	v_mfma_f32_32x32x16_bf16 v[0:15], v[84:87], v[64:67], v[0:15]
	s_nop 5
	v_mov_b64_e32 v[126:127], v[62:63]
	s_nop 0
	v_mov_b64_e32 v[110:111], v[46:47]
	s_nop 0
	v_mov_b64_e32 v[94:95], v[30:31]
	s_nop 0
	v_mov_b64_e32 v[78:79], v[14:15]
	v_mov_b64_e32 v[124:125], v[60:61]
	v_mov_b64_e32 v[122:123], v[58:59]
	v_mov_b64_e32 v[120:121], v[56:57]
	v_mov_b64_e32 v[118:119], v[54:55]
	v_mov_b64_e32 v[116:117], v[52:53]
	v_mov_b64_e32 v[114:115], v[50:51]
	v_mov_b64_e32 v[112:113], v[48:49]
	v_mov_b64_e32 v[108:109], v[44:45]
	v_mov_b64_e32 v[106:107], v[42:43]
	v_mov_b64_e32 v[104:105], v[40:41]
	v_mov_b64_e32 v[102:103], v[38:39]
	v_mov_b64_e32 v[100:101], v[36:37]
	v_mov_b64_e32 v[98:99], v[34:35]
	v_mov_b64_e32 v[96:97], v[32:33]
	v_mov_b64_e32 v[92:93], v[28:29]
	v_mov_b64_e32 v[90:91], v[26:27]
	v_mov_b64_e32 v[88:89], v[24:25]
	v_mov_b64_e32 v[86:87], v[22:23]
	v_mov_b64_e32 v[84:85], v[20:21]
	v_mov_b64_e32 v[82:83], v[18:19]
	v_mov_b64_e32 v[80:81], v[16:17]
	v_mov_b64_e32 v[76:77], v[12:13]
	v_mov_b64_e32 v[74:75], v[10:11]
	v_mov_b64_e32 v[72:73], v[8:9]
	v_mov_b64_e32 v[70:71], v[6:7]
	v_mov_b64_e32 v[68:69], v[4:5]
	v_mov_b64_e32 v[66:67], v[2:3]
	v_mov_b64_e32 v[64:65], v[0:1]
	s_and_saveexec_b64 s[70:71], s[12:13]
	s_cbranch_execnz .LBB0_817
	s_branch .LBB0_818

; __device__ __forceinline__ int diff_item(ldsp lds, int qt, int bh, bool pre, unsigned* nctr, const bf16* U, bf16* O, const float* subw, float lam, float omlinit, float M0, int wave, int lane) {
;     ...
;     {
;         const int stage = (qt & 1) * 65536;
;         unsigned nt = 0u; if (wave == 0 && lane == 0) nt = atomicAdd(nctr, 1u);
;         if (wq >= 2) attn_pair<true, false>(o, lsum, qf, LA, lds0 + stage, lds0 + stage + 32768, lds0 + stage + 16384, lds0 + stage + 32768 + 16384, nslope2, -M0, (float)(t0 + r - 128 * qt - 4 * hh), (float)(t0 + r - 128 * qt - 64 - 4 * hh));
;         else attn_tile<4, true>(o, lsum, qf, LA, lds0 + stage, lds0 + stage + 32768, nslope2, -M0, (float)(t0 + r - 128 * qt - 4 * hh));
.LBB0_1854:
	v_mov_b32_e32 v193, 0
	s_and_saveexec_b64 s[64:65], s[6:7]
	s_cbranch_execz .LBB0_1858
	s_mov_b64 s[68:69], exec
	v_mbcnt_lo_u32_b32 v64, s68, 0
	v_mbcnt_hi_u32_b32 v64, s69, v64
	v_mov_b32_e32 v255, v64
	v_cmp_eq_u32_e32 vcc, 0, v64
	s_and_saveexec_b64 s[66:67], vcc
	s_cbranch_execz .LBB0_1857
	s_bcnt1_i32_b64 s4, s[68:69]
	v_mov_b32_e32 v65, s4
	global_atomic_add v254, v157, v65, s[62:63] sc0
.LBB0_1857:
	s_or_b64 exec, exec, s[66:67]
.LBB0_1858:
	s_or_b64 exec, exec, s[64:65]
	s_lshl_b32 s4, s76, 16
	s_and_b32 s66, s4, 0x10000
	s_add_i32 s66, s66, 0
	s_add_i32 s22, s66, 0x8000
	s_mov_b64 s[64:65], -1
	s_and_b64 vcc, exec, s[34:35]
	s_cbranch_vccnz .LBB0_1868
	s_andn2_b64 vcc, exec, s[64:65]
	s_cbranch_vccz .LBB0_1869

; #define ALDS __attribute__((address_space(3)))
; __device__ __forceinline__ int diff_item(ldsp lds, int qt, int bh, bool pre, unsigned* nctr, const bf16* U, bf16* O, const float* subw, float lam, float omlinit, float M0, int wave, int lane) {
;     ...
;         if (wave == 0 && lane == 0) ((ALDS unsigned*)(lds + CTL_OFF))[3] = nt;
.LBB0_1861:
	s_waitcnt vmcnt(0)
	v_readfirstlane_b32 s98, v254
	s_nop 1
	v_add_u32_e32 v193, s98, v255
	v_mov_b32_e32 v0, s73
	ds_write_b32 v0, v193

; #define ALDS __attribute__((address_space(3)))
; template <int NET, bool BIAS>
; __device__ __forceinline__ void attn_tile(f32x16 (&o)[NET], float& lsum, const bf16x8 (&qf)[4], const LaneAddr& A, unsigned kimg, unsigned vimg, float nslope2, float negM0, float dt) {
;     bf16x8 kf[2][4];
; #pragma unroll
;     for (int ks = 0; ks < 4; ++ks) { const unsigned ka = A.kb[ks] + kimg;
;         kf[0][ks] = *(const ALDS bf16x8*)(size_t)(ka); kf[1][ks] = *(const ALDS bf16x8*)(size_t)(ka + 8192u); }
;     f32x16 s[2];
; #pragma unroll
;     for (int sub = 0; sub < 2; ++sub) {
;         if (BIAS) { const float d0 = dt - 32.0f * (float)sub;
; #pragma unroll
;             for (int i = 0; i < 16; ++i) s[sub][i] = fmaf(nslope2, fabsf(d0 - (float)((i & 3) + 8 * (i >> 2))), negM0);
;         } else {
; #pragma unroll
;             for (int i = 0; i < 16; ++i) s[sub][i] = negM0;
;         }
;     }
; #pragma unroll
;     for (int ks = 0; ks < 4; ++ks) { s[0] = __builtin_amdgcn_mfma_f32_32x32x16_bf16(kf[0][ks], qf[ks], s[0], 0, 0, 0); s[1] = __builtin_amdgcn_mfma_f32_32x32x16_bf16(kf[1][ks], qf[ks], s[1], 0, 0, 0); }
;     unsigned va[NET][2];
; #pragma unroll
;     for (int et = 0; et < NET; ++et) { va[et][0] = A.vb[2 * et] + vimg; va[et][1] = A.vb[2 * et + 1] + vimg; }
.LBB0_1868:
	v_subrev_u32_e32 v64, s80, v207
	v_add_u32_e32 v64, s81, v64
	v_cvt_f32_i32_e32 v92, v64
	v_add_u32_e32 v64, s66, v167
	ds_read_b128 v[96:99], v64
	ds_read_b128 v[80:83], v64 offset:8192
	v_add_u32_e32 v114, s66, v169
	v_add_f32_e32 v64, 0xc2000000, v92
	v_add_f32_e32 v65, -1.0, v64
	v_pk_add_f32 v[66:67], v[64:65], s[50:51] op_sel_hi:[0,1]
	v_pk_add_f32 v[68:69], v[64:65], s[48:49] op_sel_hi:[0,1]
	v_pk_add_f32 v[70:71], v[64:65], s[52:53] op_sel_hi:[0,1]
	v_pk_add_f32 v[72:73], v[64:65], s[54:55] op_sel_hi:[0,1]
	v_pk_add_f32 v[74:75], v[64:65], s[56:57] op_sel_hi:[0,1]
	v_pk_add_f32 v[76:77], v[64:65], s[58:59] op_sel_hi:[0,1]
	v_pk_add_f32 v[78:79], v[64:65], s[60:61] op_sel_hi:[0,1]
	v_and_b32_e32 v67, 0x7fffffff, v67
	v_and_b32_e32 v66, 0x7fffffff, v66
	v_and_b32_e32 v69, 0x7fffffff, v69
	v_and_b32_e32 v68, 0x7fffffff, v68
	v_and_b32_e32 v71, 0x7fffffff, v71
	v_and_b32_e32 v70, 0x7fffffff, v70
	v_and_b32_e32 v73, 0x7fffffff, v73
	v_and_b32_e32 v72, 0x7fffffff, v72
	v_and_b32_e32 v75, 0x7fffffff, v75
	v_and_b32_e32 v74, 0x7fffffff, v74
	v_and_b32_e32 v77, 0x7fffffff, v77
	v_and_b32_e32 v76, 0x7fffffff, v76
	v_and_b32_e32 v79, 0x7fffffff, v79
	v_and_b32_e32 v78, 0x7fffffff, v78
	v_and_b32_e32 v64, 0x7fffffff, v64
	v_and_b32_e32 v65, 0x7fffffff, v65
	ds_read_b128 v[84:87], v114 offset:8192
	v_pk_fma_f32 v[78:79], v[200:201], v[78:79], v[190:191] op_sel_hi:[0,1,1]
	v_pk_fma_f32 v[76:77], v[200:201], v[76:77], v[188:189] op_sel_hi:[0,1,1]
	v_pk_fma_f32 v[74:75], v[200:201], v[74:75], v[186:187] op_sel_hi:[0,1,1]
	v_pk_fma_f32 v[72:73], v[200:201], v[72:73], v[184:185] op_sel_hi:[0,1,1]
	v_pk_fma_f32 v[70:71], v[200:201], v[70:71], v[182:183] op_sel_hi:[0,1,1]
	v_pk_fma_f32 v[68:69], v[200:201], v[68:69], v[180:181] op_sel_hi:[0,1,1]
	v_pk_fma_f32 v[66:67], v[200:201], v[66:67], v[178:179] op_sel_hi:[0,1,1]
	v_pk_fma_f32 v[64:65], v[200:201], v[64:65], v[174:175] op_sel_hi:[0,1,1]
	v_add_u32_e32 v115, s66, v171
	ds_read_b128 v[88:91], v115 offset:8192
	s_waitcnt lgkmcnt(2)
	v_mfma_f32_32x32x16_bf16 v[64:79], v[80:83], v[140:143], v[64:79]
	v_add_f32_e32 v93, -1.0, v92
	v_add_f32_e64 v94, v92, s50
	v_add_f32_e64 v95, v92, s51
	v_add_f32_e64 v104, v92, s48
	v_add_f32_e64 v105, v92, s49
	v_pk_add_f32 v[106:107], v[92:93], s[52:53] op_sel_hi:[0,1]
	v_pk_add_f32 v[80:81], v[92:93], s[54:55] op_sel_hi:[0,1]
	v_pk_add_f32 v[82:83], v[92:93], s[56:57] op_sel_hi:[0,1]
	v_pk_add_f32 v[108:109], v[92:93], s[58:59] op_sel_hi:[0,1]
	s_waitcnt lgkmcnt(1)
	v_mfma_f32_32x32x16_bf16 v[64:79], v[84:87], v[136:139], v[64:79]
	v_add_f32_e64 v110, v92, s60
	v_add_f32_e64 v111, v92, s61
	v_and_b32_e32 v113, 0x7fffffff, v95
	v_and_b32_e32 v112, 0x7fffffff, v94
	v_and_b32_e32 v105, 0x7fffffff, v105
	v_and_b32_e32 v104, 0x7fffffff, v104
	v_and_b32_e32 v85, 0x7fffffff, v107
	v_and_b32_e32 v84, 0x7fffffff, v106
	v_and_b32_e32 v81, 0x7fffffff, v81
	v_and_b32_e32 v80, 0x7fffffff, v80
	v_and_b32_e32 v83, 0x7fffffff, v83
	v_and_b32_e32 v82, 0x7fffffff, v82
	s_waitcnt lgkmcnt(0)
	v_mfma_f32_32x32x16_bf16 v[64:79], v[88:91], v[132:135], v[64:79]
	v_and_b32_e32 v87, 0x7fffffff, v109
	v_and_b32_e32 v86, 0x7fffffff, v108
	v_and_b32_e32 v89, 0x7fffffff, v111
	v_and_b32_e32 v88, 0x7fffffff, v110
	v_and_b32_e32 v106, 0x7fffffff, v92
	v_and_b32_e32 v107, 0x7fffffff, v93
	v_pk_fma_f32 v[94:95], v[200:201], v[88:89], v[190:191] op_sel_hi:[0,1,1]
	v_pk_fma_f32 v[92:93], v[200:201], v[86:87], v[188:189] op_sel_hi:[0,1,1]
	v_pk_fma_f32 v[90:91], v[200:201], v[82:83], v[186:187] op_sel_hi:[0,1,1]
	v_pk_fma_f32 v[88:89], v[200:201], v[80:81], v[184:185] op_sel_hi:[0,1,1]
	v_pk_fma_f32 v[86:87], v[200:201], v[84:85], v[182:183] op_sel_hi:[0,1,1]
	v_pk_fma_f32 v[84:85], v[200:201], v[104:105], v[180:181] op_sel_hi:[0,1,1]
	v_pk_fma_f32 v[82:83], v[200:201], v[112:113], v[178:179] op_sel_hi:[0,1,1]
	v_pk_fma_f32 v[80:81], v[200:201], v[106:107], v[174:175] op_sel_hi:[0,1,1]
	v_add_u32_e32 v116, s66, v173
	ds_read_b128 v[100:103], v116 offset:8192
	v_mfma_f32_32x32x16_bf16 v[80:95], v[96:99], v[140:143], v[80:95]
	ds_read_b128 v[96:99], v114
	v_add_u32_e32 v145, s22, v159
	v_add_u32_e32 v150, s22, v202
	v_add_u32_e32 v151, s22, v161
	v_add_u32_e32 v197, s22, v203
	v_add_u32_e32 v199, s22, v163
	v_add_u32_e32 v213, s22, v204
	s_waitcnt lgkmcnt(0)
	v_mfma_f32_32x32x16_bf16 v[80:95], v[96:99], v[136:139], v[80:95]
	v_add_u32_e32 v242, s22, v165
	v_add_u32_e32 v243, s22, v205
	s_nop 0
	v_mfma_f32_32x32x16_bf16 v[64:79], v[100:103], v[128:131], v[64:79]
	ds_read_b128 v[96:99], v115
	ds_read_b128 v[100:103], v116
	s_waitcnt lgkmcnt(1)
	v_mfma_f32_32x32x16_bf16 v[80:95], v[96:99], v[132:135], v[80:95]
	s_nop 7
	v_exp_f32_e32 v64, v64
	v_exp_f32_e32 v65, v65
	v_exp_f32_e32 v66, v66
	v_exp_f32_e32 v67, v67
	v_exp_f32_e32 v68, v68
	v_exp_f32_e32 v69, v69
	v_exp_f32_e32 v70, v70
	s_waitcnt lgkmcnt(0)
; #define TR_ISSUE(dst, addr, OFF) dst = vtr((ldsp)(size_t)((addr) + (unsigned)(OFF)))
; template <int NET, bool BIAS>
; __device__ __forceinline__ void attn_tile(f32x16 (&o)[NET], float& lsum, const bf16x8 (&qf)[4], const LaneAddr& A, unsigned kimg, unsigned vimg, float nslope2, float negM0, float dt) {
;     ...
;     s16x4 vlo[2][NET], vhi[2][NET];
; #pragma unroll
;     for (int et = 0; et < NET; ++et) { TR_ISSUE(vlo[0][et], va[et][0], 0); TR_ISSUE(vhi[0][et], va[et][1], 2048); }
;     bf16x8 pa[2][2];
; #pragma unroll
;     for (int sub = 0; sub < 2; ++sub) {
; #pragma unroll
;         for (int i = 0; i < 16; ++i) { s[sub][i] = __builtin_amdgcn_exp2f(s[sub][i]); lsum += s[sub][i]; }
;         pa[sub][0] = pack8s(s[sub], 0); pa[sub][1] = pack8s(s[sub], 8);
;     }
;     tr_wait<NET>(vlo[0], vhi[0]);
;     __builtin_amdgcn_sched_barrier(0);
; #pragma unroll
;     for (int step = 0; step < 4; ++step) {
;         const int cur = step & 1, nxt = cur ^ 1;
;         if (step < 3) {
; #pragma unroll
;             for (int et = 0; et < NET; ++et) { TR_ISSUE(vlo[nxt][et], va[et][0], 256 * (32 * ((step + 1) >> 1) + 16 * ((step + 1) & 1))); TR_ISSUE(vhi[nxt][et], va[et][1], 256 * (32 * ((step + 1) >> 1) + 16 * ((step + 1) & 1)) + 2048); } }
; #pragma unroll
;         for (int et = 0; et < NET; ++et) {
;             const bf16x8 vf = (bf16x8){vlo[cur][et][0], vlo[cur][et][1], vlo[cur][et][2], vlo[cur][et][3], vhi[cur][et][0], vhi[cur][et][1], vhi[cur][et][2], vhi[cur][et][3]};
;             o[et] = __builtin_amdgcn_mfma_f32_32x32x16_bf16(vf, pa[step >> 1][step & 1], o[et], 0, 0, 0);
;         }
;         if (step < 3) tr_wait<NET>(vlo[nxt], vhi[nxt]);
;         __builtin_amdgcn_sched_barrier(0);
;     }
	v_mfma_f32_32x32x16_bf16 v[80:95], v[100:103], v[128:131], v[80:95]
	v_exp_f32_e32 v71, v71
	v_exp_f32_e32 v244, v72
	ds_read_b64_tr_b16 v[96:97], v145
	ds_read_b64_tr_b16 v[98:99], v150 offset:2048
	ds_read_b64_tr_b16 v[146:147], v151
	ds_read_b64_tr_b16 v[148:149], v197 offset:2048
	ds_read_b64_tr_b16 v[214:215], v199
	ds_read_b64_tr_b16 v[216:217], v213 offset:2048
	ds_read_b64_tr_b16 v[218:219], v242
	ds_read_b64_tr_b16 v[220:221], v243 offset:2048
	v_exp_f32_e32 v245, v73
	v_exp_f32_e32 v246, v74
	v_exp_f32_e32 v247, v75
	v_exp_f32_e32 v248, v76
	v_exp_f32_e32 v80, v80
	v_exp_f32_e32 v81, v81
	v_exp_f32_e32 v82, v82
	v_exp_f32_e32 v83, v83
	v_add_f32_e32 v100, v195, v80
	v_exp_f32_e32 v84, v84
	v_add_f32_e32 v100, v81, v100
	v_exp_f32_e32 v85, v85
	v_add_f32_e32 v100, v82, v100
	v_exp_f32_e32 v86, v86
	v_add_f32_e32 v100, v83, v100
	v_exp_f32_e32 v87, v87
	v_add_f32_e32 v100, v84, v100
	v_exp_f32_e32 v88, v88
	v_add_f32_e32 v100, v85, v100
	v_exp_f32_e32 v89, v89
	v_add_f32_e32 v100, v86, v100
	v_exp_f32_e32 v90, v90
	v_add_f32_e32 v100, v87, v100
	v_exp_f32_e32 v91, v91
	v_add_f32_e32 v100, v88, v100
	v_exp_f32_e32 v92, v92
	v_add_f32_e32 v100, v89, v100
	v_exp_f32_e32 v93, v93
	v_add_f32_e32 v100, v90, v100
	v_exp_f32_e32 v94, v94
	v_add_f32_e32 v100, v91, v100
	v_exp_f32_e32 v95, v95
	v_add_f32_e32 v100, v92, v100
	v_add_f32_e32 v100, v93, v100
	v_add_f32_e32 v100, v94, v100
	v_add_f32_e32 v100, v95, v100
	v_cvt_pk_bf16_f32 v222, v80, v81
	v_add_f32_e32 v80, v64, v100
	v_add_f32_e32 v80, v65, v80
	v_add_f32_e32 v80, v66, v80
	v_add_f32_e32 v80, v67, v80
	v_add_f32_e32 v80, v68, v80
	v_add_f32_e32 v80, v69, v80
	v_add_f32_e32 v80, v70, v80
	v_add_f32_e32 v80, v71, v80
	v_add_f32_e32 v72, v244, v80
	v_add_f32_e32 v72, v245, v72
	v_exp_f32_e32 v249, v77
	v_add_f32_e32 v72, v246, v72
	v_exp_f32_e32 v250, v78
	v_add_f32_e32 v72, v247, v72
	v_exp_f32_e32 v251, v79
	v_add_f32_e32 v72, v248, v72
	v_add_f32_e32 v72, v249, v72
	v_add_f32_e32 v72, v250, v72
	v_add_f32_e32 v144, v251, v72
	v_cvt_pk_bf16_f32 v223, v82, v83
	v_cvt_pk_bf16_f32 v224, v84, v85
	v_cvt_pk_bf16_f32 v225, v86, v87
	v_cvt_pk_bf16_f32 v226, v88, v89
	v_cvt_pk_bf16_f32 v227, v90, v91
	v_cvt_pk_bf16_f32 v228, v92, v93
	v_cvt_pk_bf16_f32 v229, v94, v95
	v_cvt_pk_bf16_f32 v230, v64, v65
	v_cvt_pk_bf16_f32 v231, v66, v67
	v_cvt_pk_bf16_f32 v232, v68, v69
	v_cvt_pk_bf16_f32 v233, v70, v71
	s_waitcnt lgkmcnt(6)
	v_mfma_f32_32x32x16_bf16 v[112:127], v[96:99], v[222:225], v[48:63]
	s_waitcnt lgkmcnt(4)
	v_mfma_f32_32x32x16_bf16 v[96:111], v[146:149], v[222:225], v[32:47]
	ds_read_b64_tr_b16 v[146:147], v145 offset:4096
	s_waitcnt lgkmcnt(3)
	v_mfma_f32_32x32x16_bf16 v[80:95], v[214:217], v[222:225], v[16:31]
	ds_read_b64_tr_b16 v[148:149], v150 offset:6144
	ds_read_b64_tr_b16 v[214:215], v151 offset:4096
	ds_read_b64_tr_b16 v[216:217], v197 offset:6144
	ds_read_b64_tr_b16 v[234:235], v199 offset:4096
	ds_read_b64_tr_b16 v[236:237], v213 offset:6144
	ds_read_b64_tr_b16 v[238:239], v242 offset:4096
	ds_read_b64_tr_b16 v[240:241], v243 offset:6144
	s_waitcnt lgkmcnt(8)
	v_mfma_f32_32x32x16_bf16 v[64:79], v[218:221], v[222:225], v[0:15]
	s_waitcnt lgkmcnt(6)
	v_mfma_f32_32x32x16_bf16 v[112:127], v[146:149], v[226:229], v[112:127]
	ds_read_b64_tr_b16 v[146:147], v145 offset:8192
	s_waitcnt lgkmcnt(5)
	v_mfma_f32_32x32x16_bf16 v[96:111], v[214:217], v[226:229], v[96:111]
	ds_read_b64_tr_b16 v[148:149], v150 offset:10240
	ds_read_b64_tr_b16 v[214:215], v151 offset:8192
	ds_read_b64_tr_b16 v[216:217], v197 offset:10240
	ds_read_b64_tr_b16 v[218:219], v199 offset:8192
	ds_read_b64_tr_b16 v[220:221], v213 offset:10240
	ds_read_b64_tr_b16 v[222:223], v242 offset:8192
	ds_read_b64_tr_b16 v[224:225], v243 offset:10240
	s_waitcnt lgkmcnt(10)
	v_mfma_f32_32x32x16_bf16 v[80:95], v[234:237], v[226:229], v[80:95]
	s_waitcnt lgkmcnt(8)
	v_mfma_f32_32x32x16_bf16 v[64:79], v[238:241], v[226:229], v[64:79]
	s_waitcnt lgkmcnt(6)
	v_mfma_f32_32x32x16_bf16 v[112:127], v[146:149], v[230:233], v[112:127]
	ds_read_b64_tr_b16 v[146:147], v145 offset:12288
	s_waitcnt lgkmcnt(5)
	v_mfma_f32_32x32x16_bf16 v[96:111], v[214:217], v[230:233], v[96:111]
	s_waitcnt lgkmcnt(3)
	v_mfma_f32_32x32x16_bf16 v[80:95], v[218:221], v[230:233], v[80:95]
	ds_read_b64_tr_b16 v[148:149], v150 offset:14336
	ds_read_b64_tr_b16 v[214:215], v151 offset:12288
	ds_read_b64_tr_b16 v[216:217], v197 offset:14336
	ds_read_b64_tr_b16 v[218:219], v199 offset:12288
	ds_read_b64_tr_b16 v[220:221], v213 offset:14336
	ds_read_b64_tr_b16 v[226:227], v242 offset:12288
	ds_read_b64_tr_b16 v[228:229], v243 offset:14336
	s_waitcnt lgkmcnt(8)
	v_mfma_f32_32x32x16_bf16 v[64:79], v[222:225], v[230:233], v[64:79]
	v_cvt_pk_bf16_f32 v222, v244, v245
	v_cvt_pk_bf16_f32 v223, v246, v247
	v_cvt_pk_bf16_f32 v224, v248, v249
	v_cvt_pk_bf16_f32 v225, v250, v251
	s_waitcnt lgkmcnt(6)
	s_nop 0
	v_mfma_f32_32x32x16_bf16 v[112:127], v[146:149], v[222:225], v[112:127]
	s_waitcnt lgkmcnt(4)
	v_mfma_f32_32x32x16_bf16 v[96:111], v[214:217], v[222:225], v[96:111]
	s_waitcnt lgkmcnt(2)
	v_mfma_f32_32x32x16_bf16 v[80:95], v[218:221], v[222:225], v[80:95]
	s_waitcnt lgkmcnt(0)
	v_mfma_f32_32x32x16_bf16 v[64:79], v[226:229], v[222:225], v[64:79]
	s_cbranch_execnz .LBB0_1860
; #define ALDS __attribute__((address_space(3)))
; #define MF32(acc, a, b) acc = __builtin_amdgcn_mfma_f32_32x32x16_bf16(a, b, acc, 0, 0, 0)
; #define SBAR0() __builtin_amdgcn_sched_barrier(0)
; __device__ __forceinline__ void bias_tile(f32x16 (&s)[2], float nslope2, float negM0, float dt) {
; #pragma unroll
;     for (int sub = 0; sub < 2; ++sub) { const float d0 = dt - 32.0f * (float)sub;
; #pragma unroll
;         for (int i = 0; i < 16; ++i) s[sub][i] = fmaf(nslope2, fabsf(d0 - (float)((i & 3) + 8 * (i >> 2))), negM0); }
; }
; __device__ __forceinline__ void bias_tile_past(f32x16 (&s)[2], float nslope2, float negM0, float dt) {
;     const float slope2 = -nslope2;
; #pragma unroll
;     for (int sub = 0; sub < 2; ++sub) { const float cb = fmaf(nslope2, dt - 32.0f * (float)sub, negM0);
; #pragma unroll
;         for (int i = 0; i < 16; ++i) asm("v_fmamk_f32 %0, %1, %3, %2" : "=v"(s[sub][i]) : "v"(slope2), "v"(cb), "i"(__builtin_bit_cast(int, (float)((i & 3) + 8 * (i >> 2))))); }
; }
; template <bool PAST, bool PAST1 = PAST>
; __device__ __forceinline__ void attn_pair(f32x16 (&o)[4], float& lsum, const bf16x8 (&qf)[4], const LaneAddr& A, unsigned k0, unsigned v0, unsigned k1, unsigned v1, float nslope2, float negM0, float dt0, float dt1) {
;     bf16x8 kf[2][4];
;     f32x16 s0[2], s1[2];
;     bf16x8 pa0[2][2], pa1[2][2];
;     s16x4 vlo[2][4], vhi[2][4];
; #pragma unroll
;     for (int ks = 0; ks < 4; ++ks) { const unsigned ka = A.kb[ks] + k0; kf[0][ks] = *(const ALDS bf16x8*)(size_t)(ka); kf[1][ks] = *(const ALDS bf16x8*)(size_t)(ka + 8192u); }
;     if (PAST) bias_tile_past(s0, nslope2, negM0, dt0); else bias_tile(s0, nslope2, negM0, dt0);
; #pragma unroll
;     for (int ks = 0; ks < 4; ++ks) { MF32(s0[0], kf[0][ks], qf[ks]); MF32(s0[1], kf[1][ks], qf[ks]); }
;     SBAR0();
;     if (PAST1) bias_tile_past(s1, nslope2, negM0, dt1); else bias_tile(s1, nslope2, negM0, dt1);
;     unsigned va0[4][2];
; #pragma unroll
;     for (int et = 0; et < 4; ++et) { va0[et][0] = A.vb[2 * et] + v0; va0[et][1] = A.vb[2 * et + 1] + v0; }
;     bf16x8 k2[2][2];
;     { const unsigned ka = A.kb[0] + k1; k2[0][0] = *(const ALDS bf16x8*)(size_t)(ka); k2[0][1] = *(const ALDS bf16x8*)(size_t)(ka + 8192u); }
;     SBAR0();
.LBB0_1869:
	s_nop 10
	v_or_b32_e32 v64, s81, v154
	v_subrev_u32_e32 v65, s80, v206
	v_add_u32_e32 v64, v64, v65
	v_cvt_f32_i32_e32 v65, v64
	v_add_u32_e32 v66, s66, v167
	ds_read_b128 v[70:73], v66
	ds_read_b128 v[74:77], v66 offset:8192
	v_add_u32_e32 v78, s66, v169
	v_add_u32_e32 v82, s66, v171
	v_add_u32_e32 v86, s66, v173
	v_fma_f32 v91, v200, v65, v174
	v_add_f32_e32 v65, 0xc2000000, v65
	ds_read_b128 v[66:69], v78
	ds_read_b128 v[78:81], v78 offset:8192
	ds_read_b128 v[148:151], v82
	ds_read_b128 v[82:85], v82 offset:8192
	ds_read_b128 v[144:147], v86
	ds_read_b128 v[86:89], v86 offset:8192
	v_xor_b32_e32 v90, 0x80000000, v200
	v_fmamk_f32 v112, v90, 0, v91
	v_fmamk_f32 v113, v90, 0x3f800000, v91
	v_fmamk_f32 v114, v90, 0x40000000, v91
	v_fmamk_f32 v115, v90, 0x40400000, v91
	v_fmamk_f32 v116, v90, 0x41000000, v91
	v_fmamk_f32 v117, v90, 0x41100000, v91
	v_fmamk_f32 v118, v90, 0x41200000, v91
	v_fmamk_f32 v119, v90, 0x41300000, v91
	v_fmamk_f32 v120, v90, 0x41800000, v91
	v_fmamk_f32 v121, v90, 0x41880000, v91
	v_fmamk_f32 v122, v90, 0x41900000, v91
	v_fmamk_f32 v123, v90, 0x41980000, v91
	v_fmamk_f32 v124, v90, 0x41c00000, v91
	v_fmamk_f32 v125, v90, 0x41c80000, v91
	v_fmamk_f32 v126, v90, 0x41d00000, v91
	v_fmamk_f32 v127, v90, 0x41d80000, v91
	v_fma_f32 v65, v200, v65, v174
	v_fmamk_f32 v96, v90, 0, v65
	v_fmamk_f32 v97, v90, 0x3f800000, v65
	v_fmamk_f32 v98, v90, 0x40000000, v65
	v_fmamk_f32 v99, v90, 0x40400000, v65
	v_fmamk_f32 v100, v90, 0x41000000, v65
	v_fmamk_f32 v101, v90, 0x41100000, v65
	v_fmamk_f32 v102, v90, 0x41200000, v65
	v_fmamk_f32 v103, v90, 0x41300000, v65
	v_fmamk_f32 v104, v90, 0x41800000, v65
	v_fmamk_f32 v105, v90, 0x41880000, v65
	v_fmamk_f32 v106, v90, 0x41900000, v65
	v_fmamk_f32 v107, v90, 0x41980000, v65
	v_fmamk_f32 v108, v90, 0x41c00000, v65
	v_fmamk_f32 v109, v90, 0x41c80000, v65
	v_fmamk_f32 v110, v90, 0x41d00000, v65
	v_fmamk_f32 v111, v90, 0x41d80000, v65
	v_subrev_u32_e32 v64, 64, v64
	s_waitcnt lgkmcnt(6)
	v_mfma_f32_32x32x16_bf16 v[96:111], v[74:77], v[140:143], v[96:111]
	v_cvt_f32_i32_e32 v64, v64
	s_add_i32 s65, s66, 0x4000
	s_add_i32 s64, s66, 0xc000
	s_waitcnt lgkmcnt(4)
	v_mfma_f32_32x32x16_bf16 v[96:111], v[78:81], v[136:139], v[96:111]
	s_waitcnt lgkmcnt(2)
	v_mfma_f32_32x32x16_bf16 v[96:111], v[82:85], v[132:135], v[96:111]
	s_waitcnt lgkmcnt(0)
	v_mfma_f32_32x32x16_bf16 v[96:111], v[86:89], v[128:131], v[96:111]
	v_mfma_f32_32x32x16_bf16 v[112:127], v[70:73], v[140:143], v[112:127]
	v_add_f32_e32 v65, -1.0, v64
	v_add_f32_e64 v80, v64, s54
	v_add_f32_e64 v81, v64, s55
	v_add_f32_e64 v74, v64, s50
	v_add_f32_e64 v75, v64, s51
	v_pk_add_f32 v[76:77], v[64:65], s[48:49] op_sel_hi:[0,1]
	v_pk_add_f32 v[78:79], v[64:65], s[52:53] op_sel_hi:[0,1]
	v_pk_add_f32 v[82:83], v[64:65], s[56:57] op_sel_hi:[0,1]
	v_pk_add_f32 v[84:85], v[64:65], s[58:59] op_sel_hi:[0,1]
	v_mfma_f32_32x32x16_bf16 v[112:127], v[66:69], v[136:139], v[112:127]
	v_add_f32_e64 v86, v64, s60
	v_add_f32_e64 v87, v64, s61
	v_and_b32_e32 v88, 0x7fffffff, v80
	v_and_b32_e32 v80, 0x7fffffff, v64
	v_add_f32_e32 v64, 0xc2000000, v64
	v_and_b32_e32 v77, 0x7fffffff, v77
	v_and_b32_e32 v76, 0x7fffffff, v76
	v_and_b32_e32 v89, 0x7fffffff, v81
	v_mfma_f32_32x32x16_bf16 v[112:127], v[148:151], v[132:135], v[112:127]
	v_and_b32_e32 v85, 0x7fffffff, v85
	v_and_b32_e32 v84, 0x7fffffff, v84
	v_and_b32_e32 v81, 0x7fffffff, v65
	v_add_f32_e32 v65, -1.0, v64
	v_and_b32_e32 v75, 0x7fffffff, v75
	v_and_b32_e32 v74, 0x7fffffff, v74
	v_and_b32_e32 v79, 0x7fffffff, v79
	v_mfma_f32_32x32x16_bf16 v[112:127], v[144:147], v[128:131], v[112:127]
	v_and_b32_e32 v78, 0x7fffffff, v78
	v_and_b32_e32 v83, 0x7fffffff, v83
	v_and_b32_e32 v82, 0x7fffffff, v82
	v_and_b32_e32 v87, 0x7fffffff, v87
	v_and_b32_e32 v86, 0x7fffffff, v86
	v_pk_fma_f32 v[92:93], v[200:201], v[84:85], v[188:189] op_sel_hi:[0,1,1]
	v_pk_fma_f32 v[84:85], v[200:201], v[76:77], v[180:181] op_sel_hi:[0,1,1]
	v_pk_add_f32 v[76:77], v[64:65], s[48:49] op_sel_hi:[0,1]
	v_pk_add_f32 v[214:215], v[64:65], s[54:55] op_sel_hi:[0,1]
	v_pk_add_f32 v[218:219], v[64:65], s[58:59] op_sel_hi:[0,1]
	v_pk_fma_f32 v[94:95], v[200:201], v[86:87], v[190:191] op_sel_hi:[0,1,1]
	v_pk_fma_f32 v[90:91], v[200:201], v[82:83], v[186:187] op_sel_hi:[0,1,1]
	v_pk_fma_f32 v[86:87], v[200:201], v[78:79], v[182:183] op_sel_hi:[0,1,1]
	v_pk_fma_f32 v[82:83], v[200:201], v[74:75], v[178:179] op_sel_hi:[0,1,1]
	v_pk_add_f32 v[74:75], v[64:65], s[50:51] op_sel_hi:[0,1]
	v_pk_add_f32 v[78:79], v[64:65], s[52:53] op_sel_hi:[0,1]
	v_pk_add_f32 v[216:217], v[64:65], s[56:57] op_sel_hi:[0,1]
	v_pk_add_f32 v[220:221], v[64:65], s[60:61] op_sel_hi:[0,1]
	v_and_b32_e32 v224, 0x7fffffff, v76
	v_and_b32_e32 v215, 0x7fffffff, v215
	v_and_b32_e32 v214, 0x7fffffff, v214
	v_and_b32_e32 v76, 0x7fffffff, v218
	v_add_u32_e32 v218, s65, v167
	v_and_b32_e32 v223, 0x7fffffff, v75
	v_and_b32_e32 v222, 0x7fffffff, v74
	v_and_b32_e32 v225, 0x7fffffff, v77
	v_and_b32_e32 v227, 0x7fffffff, v79
	v_and_b32_e32 v226, 0x7fffffff, v78
	v_and_b32_e32 v75, 0x7fffffff, v217
	v_and_b32_e32 v74, 0x7fffffff, v216
	v_and_b32_e32 v77, 0x7fffffff, v219
	v_and_b32_e32 v79, 0x7fffffff, v221
	v_and_b32_e32 v78, 0x7fffffff, v220
	v_pk_fma_f32 v[72:73], v[200:201], v[214:215], v[184:185] op_sel_hi:[0,1,1]
	ds_read_b128 v[214:217], v218
	ds_read_b128 v[218:221], v218 offset:8192
	v_and_b32_e32 v64, 0x7fffffff, v64
	v_and_b32_e32 v65, 0x7fffffff, v65
	v_pk_fma_f32 v[80:81], v[200:201], v[80:81], v[174:175] op_sel_hi:[0,1,1]
	v_pk_fma_f32 v[88:89], v[200:201], v[88:89], v[184:185] op_sel_hi:[0,1,1]
	v_pk_fma_f32 v[64:65], v[200:201], v[64:65], v[174:175] op_sel_hi:[0,1,1]
	v_pk_fma_f32 v[78:79], v[200:201], v[78:79], v[190:191] op_sel_hi:[0,1,1]
	v_pk_fma_f32 v[76:77], v[200:201], v[76:77], v[188:189] op_sel_hi:[0,1,1]
	v_pk_fma_f32 v[74:75], v[200:201], v[74:75], v[186:187] op_sel_hi:[0,1,1]
	v_pk_fma_f32 v[70:71], v[200:201], v[226:227], v[182:183] op_sel_hi:[0,1,1]
	v_pk_fma_f32 v[68:69], v[200:201], v[224:225], v[180:181] op_sel_hi:[0,1,1]
	v_pk_fma_f32 v[66:67], v[200:201], v[222:223], v[178:179] op_sel_hi:[0,1,1]
	v_add_u32_e32 v197, s22, v159
	v_add_u32_e32 v199, s22, v202
	v_add_u32_e32 v200, s22, v161
	v_add_u32_e32 v213, s22, v203
	v_add_u32_e32 v148, s22, v163
	v_add_u32_e32 v149, s22, v204
	v_add_u32_e32 v150, s22, v165
	v_add_u32_e32 v151, s22, v205
	s_waitcnt lgkmcnt(1)
; #define ALDS __attribute__((address_space(3)))
; #define SBAR0() __builtin_amdgcn_sched_barrier(0)
; template <bool PAST, bool PAST1 = PAST>
; __device__ __forceinline__ void attn_pair(f32x16 (&o)[4], float& lsum, const bf16x8 (&qf)[4], const LaneAddr& A, unsigned k0, unsigned v0, unsigned k1, unsigned v1, float nslope2, float negM0, float dt0, float dt1) {
;     ...
; #pragma unroll
;     for (int g = 0; g < 8; ++g) {
;         const int ks = g >> 1, sub = g & 1;
;         if (sub == 0 && ks < 3) { const unsigned ka = A.kb[ks + 1] + k1; k2[(ks + 1) & 1][0] = *(const ALDS bf16x8*)(size_t)(ka); k2[(ks + 1) & 1][1] = *(const ALDS bf16x8*)(size_t)(ka + 8192u); }
;         MF32(s1[sub], k2[ks & 1][sub], qf[ks]);
; #pragma unroll
;         for (int k = 0; k < 4; ++k) { const int idx = 4 * g + k; s0[idx >> 4][idx & 15] = __builtin_amdgcn_exp2f(s0[idx >> 4][idx & 15]); lsum += s0[idx >> 4][idx & 15]; }
;         if (g & 1) pa0[g >> 2][(g >> 1) & 1] = pack8s(s0[g >> 2], 8 * ((g >> 1) & 1));
;         if (g == 6) {
; #pragma unroll
;             for (int et = 0; et < 4; ++et) { TR_ISSUE(vlo[0][et], va0[et][0], 0); TR_ISSUE(vhi[0][et], va0[et][1], 2048); } }
;         SBAR0();
;     }
;     tr_wait<4>(vlo[0], vhi[0]);
;     SBAR0();
;     unsigned va1[4][2];
; #pragma unroll
;     for (int g = 0; g < 16; ++g) {
;         const int step = g >> 2, et = g & 3, cur = step & 1, nxt = cur ^ 1;
;         if (et == 0) {
;             if (step < 3) {
; #pragma unroll
;                 for (int e2 = 0; e2 < 4; ++e2) { TR_ISSUE(vlo[nxt][e2], va0[e2][0], 256 * (32 * ((step + 1) >> 1) + 16 * ((step + 1) & 1))); TR_ISSUE(vhi[nxt][e2], va0[e2][1], 256 * (32 * ((step + 1) >> 1) + 16 * ((step + 1) & 1)) + 2048); }
;             } else {
; #pragma unroll
;                 for (int e2 = 0; e2 < 4; ++e2) { va1[e2][0] = A.vb[2 * e2] + v1; va1[e2][1] = A.vb[2 * e2 + 1] + v1; TR_ISSUE(vlo[nxt][e2], va1[e2][0], 0); TR_ISSUE(vhi[nxt][e2], va1[e2][1], 2048); }
;             }
;         }
;         MF32(o[et], VFRAG(cur, et), pa0[step >> 1][step & 1]);
; #pragma unroll
;         for (int k = 0; k < 2; ++k) { const int idx = 2 * g + k; s1[idx >> 4][idx & 15] = __builtin_amdgcn_exp2f(s1[idx >> 4][idx & 15]); lsum += s1[idx >> 4][idx & 15]; }
;         if (et == 3) { pa1[step >> 1][step & 1] = pack8s(s1[step >> 1], 8 * (step & 1)); tr_wait<4>(vlo[nxt], vhi[nxt]); }
;         SBAR0();
;     }
	v_mfma_f32_32x32x16_bf16 v[80:95], v[214:217], v[140:143], v[80:95]
	v_exp_f32_e32 v112, v112
	v_add_u32_e32 v222, s65, v169
	v_exp_f32_e32 v113, v113
	ds_read_b128 v[144:147], v222
	ds_read_b128 v[222:225], v222 offset:8192
	v_exp_f32_e32 v114, v114
	v_exp_f32_e32 v115, v115
	v_add_f32_e32 v195, v195, v112
	v_add_f32_e32 v195, v113, v195
	v_add_f32_e32 v195, v114, v195
	v_add_f32_e32 v195, v115, v195
	s_waitcnt lgkmcnt(2)
	v_mfma_f32_32x32x16_bf16 v[64:79], v[218:221], v[140:143], v[64:79]
	v_exp_f32_e32 v140, v116
	v_exp_f32_e32 v141, v117
	v_exp_f32_e32 v142, v118
	v_exp_f32_e32 v119, v119
	v_add_f32_e32 v116, v140, v195
	v_add_f32_e32 v116, v141, v116
	v_add_f32_e32 v116, v142, v116
	v_add_f32_e32 v195, v119, v116
	v_cvt_pk_bf16_f32 v116, v112, v113
	v_cvt_pk_bf16_f32 v117, v114, v115
	v_cvt_pk_bf16_f32 v118, v140, v141
	v_cvt_pk_bf16_f32 v119, v142, v119
	v_add_u32_e32 v112, s65, v171
	ds_read_b128 v[140:143], v112
	ds_read_b128 v[214:217], v112 offset:8192
	v_exp_f32_e32 v112, v120
	s_waitcnt lgkmcnt(3)
	v_mfma_f32_32x32x16_bf16 v[80:95], v[144:147], v[136:139], v[80:95]
	v_exp_f32_e32 v113, v121
	v_exp_f32_e32 v114, v122
	v_exp_f32_e32 v115, v123
	v_add_f32_e32 v120, v112, v195
	v_add_f32_e32 v120, v113, v120
	v_add_f32_e32 v120, v114, v120
	v_add_f32_e32 v120, v115, v120
	s_waitcnt lgkmcnt(2)
	v_mfma_f32_32x32x16_bf16 v[64:79], v[222:225], v[136:139], v[64:79]
	v_exp_f32_e32 v121, v124
	v_exp_f32_e32 v122, v125
	v_exp_f32_e32 v123, v126
	v_exp_f32_e32 v124, v127
	v_add_f32_e32 v120, v121, v120
	v_add_f32_e32 v120, v122, v120
	v_add_f32_e32 v120, v123, v120
	v_cvt_pk_bf16_f32 v112, v112, v113
	v_cvt_pk_bf16_f32 v113, v114, v115
	v_cvt_pk_bf16_f32 v114, v121, v122
	v_cvt_pk_bf16_f32 v115, v123, v124
	v_add_f32_e32 v136, v124, v120
	s_waitcnt lgkmcnt(1)
	v_mfma_f32_32x32x16_bf16 v[80:95], v[140:143], v[132:135], v[80:95]
	v_exp_f32_e32 v96, v96
	v_add_u32_e32 v124, s65, v173
	v_exp_f32_e32 v97, v97
	ds_read_b128 v[120:123], v124
	ds_read_b128 v[124:127], v124 offset:8192
	v_exp_f32_e32 v98, v98
	v_exp_f32_e32 v99, v99
	v_add_f32_e32 v136, v96, v136
	v_add_f32_e32 v136, v97, v136
	v_add_f32_e32 v136, v98, v136
	v_add_f32_e32 v136, v99, v136
	s_waitcnt lgkmcnt(2)
	v_mfma_f32_32x32x16_bf16 v[64:79], v[214:217], v[132:135], v[64:79]
	v_exp_f32_e32 v132, v100
	v_exp_f32_e32 v133, v101
	v_exp_f32_e32 v134, v102
	v_exp_f32_e32 v103, v103
	v_add_f32_e32 v100, v132, v136
	v_add_f32_e32 v100, v133, v100
	v_add_f32_e32 v100, v134, v100
	v_add_f32_e32 v135, v103, v100
	v_cvt_pk_bf16_f32 v100, v96, v97
	v_cvt_pk_bf16_f32 v101, v98, v99
	v_cvt_pk_bf16_f32 v102, v132, v133
	v_cvt_pk_bf16_f32 v103, v134, v103
	v_exp_f32_e32 v96, v104
	s_waitcnt lgkmcnt(1)
	v_mfma_f32_32x32x16_bf16 v[80:95], v[120:123], v[128:131], v[80:95]
	v_exp_f32_e32 v98, v105
	v_exp_f32_e32 v99, v106
	v_add_f32_e32 v97, v96, v135
	v_exp_f32_e32 v140, v107
	ds_read_b64_tr_b16 v[104:105], v197
	ds_read_b64_tr_b16 v[106:107], v199 offset:2048
	ds_read_b64_tr_b16 v[120:121], v200
	ds_read_b64_tr_b16 v[122:123], v213 offset:2048
	ds_read_b64_tr_b16 v[132:133], v148
	ds_read_b64_tr_b16 v[134:135], v149 offset:2048
	ds_read_b64_tr_b16 v[136:137], v150
	ds_read_b64_tr_b16 v[138:139], v151 offset:2048
	v_add_f32_e32 v97, v98, v97
	v_add_f32_e32 v97, v99, v97
	v_add_f32_e32 v97, v140, v97
	s_waitcnt lgkmcnt(8)
	v_mfma_f32_32x32x16_bf16 v[64:79], v[124:127], v[128:131], v[64:79]
	v_exp_f32_e32 v108, v108
	v_exp_f32_e32 v109, v109
	v_exp_f32_e32 v110, v110
	v_exp_f32_e32 v111, v111
	v_add_f32_e32 v97, v108, v97
	v_add_f32_e32 v97, v109, v97
	v_add_f32_e32 v97, v110, v97
	v_add_f32_e32 v144, v111, v97
	v_cvt_pk_bf16_f32 v96, v96, v98
	v_cvt_pk_bf16_f32 v97, v99, v140
	v_cvt_pk_bf16_f32 v98, v108, v109
	v_cvt_pk_bf16_f32 v99, v110, v111
	ds_read_b64_tr_b16 v[108:109], v197 offset:4096
	ds_read_b64_tr_b16 v[110:111], v199 offset:6144
	ds_read_b64_tr_b16 v[124:125], v200 offset:4096
	ds_read_b64_tr_b16 v[126:127], v213 offset:6144
	ds_read_b64_tr_b16 v[128:129], v148 offset:4096
	ds_read_b64_tr_b16 v[130:131], v149 offset:6144
	ds_read_b64_tr_b16 v[140:141], v150 offset:4096
	ds_read_b64_tr_b16 v[142:143], v151 offset:6144
	v_exp_f32_e32 v80, v80
	v_exp_f32_e32 v81, v81
	s_waitcnt lgkmcnt(14)
	v_mfma_f32_32x32x16_bf16 v[48:63], v[104:107], v[116:119], v[48:63]
	v_add_f32_e32 v104, v80, v144
	v_add_f32_e32 v104, v81, v104
	v_exp_f32_e32 v82, v82
	v_exp_f32_e32 v83, v83
	s_waitcnt lgkmcnt(12)
	v_mfma_f32_32x32x16_bf16 v[32:47], v[120:123], v[116:119], v[32:47]
	v_add_f32_e32 v104, v82, v104
	v_add_f32_e32 v104, v83, v104
	v_exp_f32_e32 v84, v84
	v_exp_f32_e32 v85, v85
	s_waitcnt lgkmcnt(10)
	v_mfma_f32_32x32x16_bf16 v[16:31], v[132:135], v[116:119], v[16:31]
	v_add_f32_e32 v104, v84, v104
	v_add_f32_e32 v104, v85, v104
	v_exp_f32_e32 v86, v86
	v_exp_f32_e32 v87, v87
	v_cvt_pk_bf16_f32 v80, v80, v81
	v_cvt_pk_bf16_f32 v81, v82, v83
	v_add_f32_e32 v104, v86, v104
	v_cvt_pk_bf16_f32 v82, v84, v85
	v_cvt_pk_bf16_f32 v83, v86, v87
	s_waitcnt lgkmcnt(8)
	v_mfma_f32_32x32x16_bf16 v[0:15], v[136:139], v[116:119], v[0:15]
	v_add_f32_e32 v136, v87, v104
	ds_read_b64_tr_b16 v[104:105], v197 offset:8192
	ds_read_b64_tr_b16 v[106:107], v199 offset:10240
	ds_read_b64_tr_b16 v[116:117], v200 offset:8192
	ds_read_b64_tr_b16 v[118:119], v213 offset:10240
	ds_read_b64_tr_b16 v[120:121], v148 offset:8192
	ds_read_b64_tr_b16 v[122:123], v149 offset:10240
	ds_read_b64_tr_b16 v[132:133], v150 offset:8192
	ds_read_b64_tr_b16 v[134:135], v151 offset:10240
	v_exp_f32_e32 v84, v88
	v_exp_f32_e32 v86, v89
	s_waitcnt lgkmcnt(14)
; #define TR_ISSUE(dst, addr, OFF) dst = vtr((ldsp)(size_t)((addr) + (unsigned)(OFF)))
; #define MF32(acc, a, b) acc = __builtin_amdgcn_mfma_f32_32x32x16_bf16(a, b, acc, 0, 0, 0)
; #define SBAR0() __builtin_amdgcn_sched_barrier(0)
; template <bool PAST, bool PAST1 = PAST>
; __device__ __forceinline__ void attn_pair(f32x16 (&o)[4], float& lsum, const bf16x8 (&qf)[4], const LaneAddr& A, unsigned k0, unsigned v0, unsigned k1, unsigned v1, float nslope2, float negM0, float dt0, float dt1) {
;     ...
;     unsigned va1[4][2];
; #pragma unroll
;     for (int g = 0; g < 16; ++g) {
;         const int step = g >> 2, et = g & 3, cur = step & 1, nxt = cur ^ 1;
;         if (et == 0) {
;             if (step < 3) {
; #pragma unroll
;                 for (int e2 = 0; e2 < 4; ++e2) { TR_ISSUE(vlo[nxt][e2], va0[e2][0], 256 * (32 * ((step + 1) >> 1) + 16 * ((step + 1) & 1))); TR_ISSUE(vhi[nxt][e2], va0[e2][1], 256 * (32 * ((step + 1) >> 1) + 16 * ((step + 1) & 1)) + 2048); }
;             } else {
; #pragma unroll
;                 for (int e2 = 0; e2 < 4; ++e2) { va1[e2][0] = A.vb[2 * e2] + v1; va1[e2][1] = A.vb[2 * e2 + 1] + v1; TR_ISSUE(vlo[nxt][e2], va1[e2][0], 0); TR_ISSUE(vhi[nxt][e2], va1[e2][1], 2048); }
;             }
;         }
;         MF32(o[et], VFRAG(cur, et), pa0[step >> 1][step & 1]);
; #pragma unroll
;         for (int k = 0; k < 2; ++k) { const int idx = 2 * g + k; s1[idx >> 4][idx & 15] = __builtin_amdgcn_exp2f(s1[idx >> 4][idx & 15]); lsum += s1[idx >> 4][idx & 15]; }
;         if (et == 3) { pa1[step >> 1][step & 1] = pack8s(s1[step >> 1], 8 * (step & 1)); tr_wait<4>(vlo[nxt], vhi[nxt]); }
;         SBAR0();
;     }
	v_mfma_f32_32x32x16_bf16 v[48:63], v[108:111], v[112:115], v[48:63]
	v_add_f32_e32 v85, v84, v136
	v_add_f32_e32 v85, v86, v85
	v_exp_f32_e32 v87, v90
	v_exp_f32_e32 v88, v91
	s_waitcnt lgkmcnt(12)
	v_mfma_f32_32x32x16_bf16 v[32:47], v[124:127], v[112:115], v[32:47]
	v_add_f32_e32 v85, v87, v85
	v_add_f32_e32 v85, v88, v85
	v_exp_f32_e32 v89, v92
	v_exp_f32_e32 v90, v93
	s_waitcnt lgkmcnt(10)
	v_mfma_f32_32x32x16_bf16 v[16:31], v[128:131], v[112:115], v[16:31]
	v_add_f32_e32 v85, v89, v85
	v_add_f32_e32 v85, v90, v85
	v_exp_f32_e32 v91, v94
	v_exp_f32_e32 v92, v95
	v_cvt_pk_bf16_f32 v84, v84, v86
	v_cvt_pk_bf16_f32 v86, v89, v90
	v_add_f32_e32 v85, v91, v85
	v_add_f32_e32 v124, v92, v85
	v_cvt_pk_bf16_f32 v85, v87, v88
	v_cvt_pk_bf16_f32 v87, v91, v92
	s_waitcnt lgkmcnt(8)
	v_mfma_f32_32x32x16_bf16 v[0:15], v[140:143], v[112:115], v[0:15]
	ds_read_b64_tr_b16 v[88:89], v197 offset:12288
	ds_read_b64_tr_b16 v[90:91], v199 offset:14336
	ds_read_b64_tr_b16 v[92:93], v200 offset:12288
	ds_read_b64_tr_b16 v[94:95], v213 offset:14336
	ds_read_b64_tr_b16 v[108:109], v148 offset:12288
	ds_read_b64_tr_b16 v[110:111], v149 offset:14336
	ds_read_b64_tr_b16 v[112:113], v150 offset:12288
	ds_read_b64_tr_b16 v[114:115], v151 offset:14336
	v_exp_f32_e32 v64, v64
	v_exp_f32_e32 v65, v65
	s_waitcnt lgkmcnt(14)
	v_mfma_f32_32x32x16_bf16 v[48:63], v[104:107], v[100:103], v[48:63]
	v_add_f32_e32 v104, v64, v124
	v_add_f32_e32 v104, v65, v104
	v_exp_f32_e32 v66, v66
	v_exp_f32_e32 v67, v67
	s_waitcnt lgkmcnt(12)
	v_mfma_f32_32x32x16_bf16 v[32:47], v[116:119], v[100:103], v[32:47]
	v_add_f32_e32 v104, v66, v104
	v_add_f32_e32 v104, v67, v104
	v_exp_f32_e32 v68, v68
	v_exp_f32_e32 v69, v69
	s_waitcnt lgkmcnt(10)
	v_mfma_f32_32x32x16_bf16 v[16:31], v[120:123], v[100:103], v[16:31]
	v_add_f32_e32 v104, v68, v104
	v_add_f32_e32 v104, v69, v104
	v_exp_f32_e32 v70, v70
	v_exp_f32_e32 v71, v71
	s_waitcnt lgkmcnt(8)
	v_mfma_f32_32x32x16_bf16 v[0:15], v[132:135], v[100:103], v[0:15]
	v_cvt_pk_bf16_f32 v64, v64, v65
	v_add_f32_e32 v100, v70, v104
	v_add_f32_e32 v120, v71, v100
	v_cvt_pk_bf16_f32 v65, v66, v67
	v_cvt_pk_bf16_f32 v66, v68, v69
	v_cvt_pk_bf16_f32 v67, v70, v71
	v_exp_f32_e32 v129, v72
	v_add_u32_e32 v121, s64, v159
	v_add_u32_e32 v123, s64, v161
	v_add_u32_e32 v125, s64, v163
	v_add_u32_e32 v127, s64, v165
	v_add_u32_e32 v122, s64, v202
	ds_read_b64_tr_b16 v[68:69], v121
	ds_read_b64_tr_b16 v[70:71], v122 offset:2048
	v_add_u32_e32 v124, s64, v203
	ds_read_b64_tr_b16 v[100:101], v123
	ds_read_b64_tr_b16 v[102:103], v124 offset:2048
	v_add_u32_e32 v126, s64, v204
	ds_read_b64_tr_b16 v[104:105], v125
	ds_read_b64_tr_b16 v[106:107], v126 offset:2048
	v_add_u32_e32 v128, s64, v205
	ds_read_b64_tr_b16 v[116:117], v127
	ds_read_b64_tr_b16 v[118:119], v128 offset:2048
	v_add_f32_e32 v72, v129, v120
	v_exp_f32_e32 v120, v73
	s_waitcnt lgkmcnt(14)
	v_mfma_f32_32x32x16_bf16 v[48:63], v[88:91], v[96:99], v[48:63]
	v_add_f32_e32 v72, v120, v72
	s_waitcnt lgkmcnt(12)
	v_mfma_f32_32x32x16_bf16 v[32:47], v[92:95], v[96:99], v[32:47]
	v_exp_f32_e32 v92, v74
	v_exp_f32_e32 v93, v75
	v_add_f32_e32 v72, v92, v72
	v_add_f32_e32 v72, v93, v72
	v_exp_f32_e32 v94, v76
	v_exp_f32_e32 v95, v77
	s_waitcnt lgkmcnt(10)
	v_mfma_f32_32x32x16_bf16 v[16:31], v[108:111], v[96:99], v[16:31]
	v_add_f32_e32 v72, v94, v72
	v_add_f32_e32 v72, v95, v72
	s_waitcnt lgkmcnt(8)
	v_mfma_f32_32x32x16_bf16 v[0:15], v[112:115], v[96:99], v[0:15]
	v_exp_f32_e32 v96, v78
	v_exp_f32_e32 v97, v79
	v_add_f32_e32 v72, v96, v72
	v_add_f32_e32 v144, v97, v72
	s_waitcnt lgkmcnt(6)
; #define TR_ISSUE(dst, addr, OFF) dst = vtr((ldsp)(size_t)((addr) + (unsigned)(OFF)))
; #define MF32(acc, a, b) acc = __builtin_amdgcn_mfma_f32_32x32x16_bf16(a, b, acc, 0, 0, 0)
; #define SBAR0() __builtin_amdgcn_sched_barrier(0)
; template <bool PAST, bool PAST1 = PAST>
; __device__ __forceinline__ void attn_pair(f32x16 (&o)[4], float& lsum, const bf16x8 (&qf)[4], const LaneAddr& A, unsigned k0, unsigned v0, unsigned k1, unsigned v1, float nslope2, float negM0, float dt0, float dt1) {
;     ...
; #pragma unroll
;     for (int step = 0; step < 4; ++step) {
;         const int cur = step & 1, nxt = cur ^ 1;
;         if (step < 3) {
; #pragma unroll
;             for (int e2 = 0; e2 < 4; ++e2) { TR_ISSUE(vlo[nxt][e2], va1[e2][0], 256 * (32 * ((step + 1) >> 1) + 16 * ((step + 1) & 1))); TR_ISSUE(vhi[nxt][e2], va1[e2][1], 256 * (32 * ((step + 1) >> 1) + 16 * ((step + 1) & 1)) + 2048); } }
; #pragma unroll
;         for (int et = 0; et < 4; ++et) MF32(o[et], VFRAG(cur, et), pa1[step >> 1][step & 1]);
;         if (step < 3) tr_wait<4>(vlo[nxt], vhi[nxt]);
;         SBAR0();
;     }
	v_mfma_f32_32x32x16_bf16 v[48:63], v[68:71], v[80:83], v[48:63]
	ds_read_b64_tr_b16 v[68:69], v121 offset:4096
	ds_read_b64_tr_b16 v[70:71], v122 offset:6144
	ds_read_b64_tr_b16 v[72:73], v123 offset:4096
	ds_read_b64_tr_b16 v[74:75], v124 offset:6144
	ds_read_b64_tr_b16 v[76:77], v125 offset:4096
	ds_read_b64_tr_b16 v[78:79], v126 offset:6144
	ds_read_b64_tr_b16 v[88:89], v127 offset:4096
	ds_read_b64_tr_b16 v[90:91], v128 offset:6144
	s_waitcnt lgkmcnt(12)
	v_mfma_f32_32x32x16_bf16 v[32:47], v[100:103], v[80:83], v[32:47]
	s_waitcnt lgkmcnt(10)
	v_mfma_f32_32x32x16_bf16 v[16:31], v[104:107], v[80:83], v[16:31]
	s_waitcnt lgkmcnt(8)
	v_mfma_f32_32x32x16_bf16 v[0:15], v[116:119], v[80:83], v[0:15]
	s_waitcnt lgkmcnt(6)
	v_mfma_f32_32x32x16_bf16 v[48:63], v[68:71], v[84:87], v[48:63]
	ds_read_b64_tr_b16 v[68:69], v121 offset:8192
	s_waitcnt lgkmcnt(5)
	v_mfma_f32_32x32x16_bf16 v[32:47], v[72:75], v[84:87], v[32:47]
	s_waitcnt lgkmcnt(3)
	v_mfma_f32_32x32x16_bf16 v[16:31], v[76:79], v[84:87], v[16:31]
	ds_read_b64_tr_b16 v[70:71], v122 offset:10240
	ds_read_b64_tr_b16 v[72:73], v123 offset:8192
	ds_read_b64_tr_b16 v[74:75], v124 offset:10240
	ds_read_b64_tr_b16 v[76:77], v125 offset:8192
	ds_read_b64_tr_b16 v[78:79], v126 offset:10240
	ds_read_b64_tr_b16 v[80:81], v127 offset:8192
	ds_read_b64_tr_b16 v[82:83], v128 offset:10240
	s_waitcnt lgkmcnt(8)
	v_mfma_f32_32x32x16_bf16 v[0:15], v[88:91], v[84:87], v[0:15]
	s_waitcnt lgkmcnt(6)
	v_mfma_f32_32x32x16_bf16 v[48:63], v[68:71], v[64:67], v[48:63]
	ds_read_b64_tr_b16 v[68:69], v121 offset:12288
	s_waitcnt lgkmcnt(5)
	v_mfma_f32_32x32x16_bf16 v[32:47], v[72:75], v[64:67], v[32:47]
	s_waitcnt lgkmcnt(3)
	v_mfma_f32_32x32x16_bf16 v[16:31], v[76:79], v[64:67], v[16:31]
	ds_read_b64_tr_b16 v[70:71], v122 offset:14336
	ds_read_b64_tr_b16 v[72:73], v123 offset:12288
	ds_read_b64_tr_b16 v[74:75], v124 offset:14336
	ds_read_b64_tr_b16 v[76:77], v125 offset:12288
	ds_read_b64_tr_b16 v[78:79], v126 offset:14336
	ds_read_b64_tr_b16 v[84:85], v127 offset:12288
	ds_read_b64_tr_b16 v[86:87], v128 offset:14336
	s_waitcnt lgkmcnt(8)
	v_mfma_f32_32x32x16_bf16 v[0:15], v[80:83], v[64:67], v[0:15]
	v_cvt_pk_bf16_f32 v64, v129, v120
	v_cvt_pk_bf16_f32 v65, v92, v93
	v_cvt_pk_bf16_f32 v66, v94, v95
	v_cvt_pk_bf16_f32 v67, v96, v97
	s_waitcnt lgkmcnt(6)
	s_nop 0
	v_mfma_f32_32x32x16_bf16 v[48:63], v[68:71], v[64:67], v[48:63]
	s_waitcnt lgkmcnt(4)
	v_mfma_f32_32x32x16_bf16 v[32:47], v[72:75], v[64:67], v[32:47]
	s_waitcnt lgkmcnt(2)
	v_mfma_f32_32x32x16_bf16 v[16:31], v[76:79], v[64:67], v[16:31]
	s_waitcnt lgkmcnt(0)
	v_mfma_f32_32x32x16_bf16 v[0:15], v[84:87], v[64:67], v[0:15]
	s_nop 5
	v_mov_b64_e32 v[126:127], v[62:63]
	s_nop 0
	v_mov_b64_e32 v[110:111], v[46:47]
	s_nop 0
	v_mov_b64_e32 v[94:95], v[30:31]
	s_nop 0
	v_mov_b64_e32 v[78:79], v[14:15]
	v_mov_b64_e32 v[124:125], v[60:61]
	v_mov_b64_e32 v[122:123], v[58:59]
	v_mov_b64_e32 v[120:121], v[56:57]
	v_mov_b64_e32 v[118:119], v[54:55]
	v_mov_b64_e32 v[116:117], v[52:53]
	v_mov_b64_e32 v[114:115], v[50:51]
	v_mov_b64_e32 v[112:113], v[48:49]
	v_mov_b64_e32 v[108:109], v[44:45]
	v_mov_b64_e32 v[106:107], v[42:43]
	v_mov_b64_e32 v[104:105], v[40:41]
	v_mov_b64_e32 v[102:103], v[38:39]
	v_mov_b64_e32 v[100:101], v[36:37]
	v_mov_b64_e32 v[98:99], v[34:35]
	v_mov_b64_e32 v[96:97], v[32:33]
	v_mov_b64_e32 v[92:93], v[28:29]
	v_mov_b64_e32 v[90:91], v[26:27]
	v_mov_b64_e32 v[88:89], v[24:25]
	v_mov_b64_e32 v[86:87], v[22:23]
	v_mov_b64_e32 v[84:85], v[20:21]
	v_mov_b64_e32 v[82:83], v[18:19]
	v_mov_b64_e32 v[80:81], v[16:17]
	v_mov_b64_e32 v[76:77], v[12:13]
	v_mov_b64_e32 v[74:75], v[10:11]
	v_mov_b64_e32 v[72:73], v[8:9]
	v_mov_b64_e32 v[70:71], v[6:7]
	v_mov_b64_e32 v[68:69], v[4:5]
	v_mov_b64_e32 v[66:67], v[2:3]
	v_mov_b64_e32 v[64:65], v[0:1]
	s_and_saveexec_b64 s[64:65], s[6:7]
	s_cbranch_execnz .LBB0_1861
	s_branch .LBB0_1862
